# all per-phase s_setprio flips deleted from the GEMM K-loops (both halves at priority 0)
# baseline (speedup 1.0000x reference)
.LBB0_162:
	s_ashr_i32 s29, s28, 31
	s_lshl_b64 s[30:31], s[28:29], 19
	s_add_u32 s30, s62, s30
	s_addc_u32 s31, s63, s31
	s_and_b64 s[34:35], s[36:37], exec
	s_cselect_b32 s29, s31, s43
	s_cselect_b32 s60, s30, s42
	s_ashr_i32 s27, s26, 31
	s_lshl_b64 s[34:35], s[26:27], 19
	s_add_u32 s34, s17, s34
	s_addc_u32 s35, s18, s35
	s_and_b64 s[44:45], s[36:37], exec
	s_cselect_b32 s27, s35, s41
	s_cselect_b32 s61, s34, s40
	s_lshl_b32 s3, s38, 8
	v_add_u32_e32 v0, s3, v141
	s_add_u32 s64, s40, 0x100
	v_ashrrev_i32_e32 v1, 31, v0
	s_addc_u32 s65, s41, 0
	v_lshl_add_u64 v[156:157], v[0:1], 2, s[72:73]
	s_add_u32 s38, s42, 0xa000
	v_mov_b32_e32 v0, 0
	s_addc_u32 s39, s43, 0
	s_mov_b32 s66, -2
	s_mov_b64 s[40:41], 0
	s_add_u32 s42, s38, 0x6000
	s_addc_u32 s43, s39, 0
	s_and_b64 s[40:41], s[40:41], exec
	s_cselect_b32 s44, s60, s42
	s_cselect_b32 s45, s29, s43
	s_cselect_b32 s43, s27, s65
	s_cselect_b32 s42, s61, s64
	s_add_u32 s40, s44, 0x8000
	s_addc_u32 s41, s45, 0
	s_add_i32 s67, 0, 0x10000
	v_add_u32_e32 v159, s67, v143
	s_add_i32 s70, 0, 0x14000
	ds_read_b128 v[160:163], v159
	ds_read_b128 v[164:167], v159 offset:1024
	ds_read_b128 v[168:171], v159 offset:2048
	ds_read_b128 v[172:175], v159 offset:3072
	v_add_u32_e32 v159, s70, v143
	ds_read_b128 v[176:179], v159
	ds_read_b128 v[180:183], v159 offset:1024
	ds_read_b128 v[184:187], v159 offset:2048
	ds_read_b128 v[188:191], v159 offset:3072
	s_add_i32 m0, s46, 0xc000
	ds_read_b128 v[192:195], v153
	ds_read_b128 v[196:199], v153 offset:1024
	ds_read_b128 v[200:203], v153 offset:2048
	ds_read_b128 v[204:207], v153 offset:3072
	ds_read_b128 v[218:221], v153 offset:4096
	ds_read_b128 v[222:225], v153 offset:5120
	ds_read_b128 v[226:229], v153 offset:6144
	ds_read_b128 v[230:233], v153 offset:7168
	global_load_lds_dwordx4 v136, s[38:39]
	s_add_i32 m0, s46, 0xe000
	s_nop 0
	global_load_lds_dwordx4 v138, s[38:39]
	s_waitcnt vmcnt(8)
	s_waitcnt lgkmcnt(0)
	s_barrier
	s_waitcnt lgkmcnt(0)
	v_mfma_f32_16x16x32_bf16 v[124:127], v[160:163], v[192:195], 0
	v_mfma_f32_16x16x32_bf16 v[120:123], v[168:171], v[192:195], 0
	v_mfma_f32_16x16x32_bf16 v[108:111], v[160:163], v[200:203], 0
	v_mfma_f32_16x16x32_bf16 v[104:107], v[168:171], v[200:203], 0
	v_mfma_f32_16x16x32_bf16 v[92:95], v[160:163], v[218:221], 0
	v_mfma_f32_16x16x32_bf16 v[88:91], v[168:171], v[218:221], 0
	v_mfma_f32_16x16x32_bf16 v[76:79], v[160:163], v[226:229], 0
	v_mfma_f32_16x16x32_bf16 v[72:75], v[168:171], v[226:229], 0
	v_mfma_f32_16x16x32_bf16 v[124:127], v[164:167], v[196:199], v[124:127]
	v_mfma_f32_16x16x32_bf16 v[120:123], v[172:175], v[196:199], v[120:123]
	v_mfma_f32_16x16x32_bf16 v[108:111], v[164:167], v[204:207], v[108:111]
	v_mfma_f32_16x16x32_bf16 v[104:107], v[172:175], v[204:207], v[104:107]
	v_mfma_f32_16x16x32_bf16 v[92:95], v[164:167], v[222:225], v[92:95]
	v_mfma_f32_16x16x32_bf16 v[88:91], v[172:175], v[222:225], v[88:91]
	v_mfma_f32_16x16x32_bf16 v[76:79], v[164:167], v[230:233], v[76:79]
	v_mfma_f32_16x16x32_bf16 v[72:75], v[172:175], v[230:233], v[72:75]
	v_mfma_f32_16x16x32_bf16 v[116:119], v[176:179], v[192:195], 0
	v_mfma_f32_16x16x32_bf16 v[112:115], v[184:187], v[192:195], 0
	v_mfma_f32_16x16x32_bf16 v[100:103], v[176:179], v[200:203], 0
	v_mfma_f32_16x16x32_bf16 v[96:99], v[184:187], v[200:203], 0
	v_mfma_f32_16x16x32_bf16 v[84:87], v[176:179], v[218:221], 0
	v_mfma_f32_16x16x32_bf16 v[80:83], v[184:187], v[218:221], 0
	v_mfma_f32_16x16x32_bf16 v[68:71], v[176:179], v[226:229], 0
	v_mfma_f32_16x16x32_bf16 v[64:67], v[184:187], v[226:229], 0
	v_mfma_f32_16x16x32_bf16 v[116:119], v[180:183], v[196:199], v[116:119]
	v_mfma_f32_16x16x32_bf16 v[112:115], v[188:191], v[196:199], v[112:115]
	v_mfma_f32_16x16x32_bf16 v[100:103], v[180:183], v[204:207], v[100:103]
	v_mfma_f32_16x16x32_bf16 v[96:99], v[188:191], v[204:207], v[96:99]
	v_mfma_f32_16x16x32_bf16 v[84:87], v[180:183], v[222:225], v[84:87]
	v_mfma_f32_16x16x32_bf16 v[80:83], v[188:191], v[222:225], v[80:83]
	v_mfma_f32_16x16x32_bf16 v[68:71], v[180:183], v[230:233], v[68:71]
	v_mfma_f32_16x16x32_bf16 v[64:67], v[188:191], v[230:233], v[64:67]
	s_barrier
	s_add_i32 s67, s67, s19
	s_mov_b32 m0, s67
	ds_read_b128 v[192:195], v153 offset:16384
	ds_read_b128 v[196:199], v153 offset:17408
	ds_read_b128 v[200:203], v153 offset:18432
	ds_read_b128 v[204:207], v153 offset:19456
	ds_read_b128 v[218:221], v153 offset:20480
	ds_read_b128 v[222:225], v153 offset:21504
	ds_read_b128 v[226:229], v153 offset:22528
	ds_read_b128 v[230:233], v153 offset:23552
	global_load_lds_dwordx4 v132, s[42:43]
	s_add_i32 m0, s67, 0x2000
	s_add_u32 s68, s42, 0x10000
	s_addc_u32 s69, s43, 0
	s_add_i32 s67, s70, s19
	global_load_lds_dwordx4 v128, s[42:43]
	s_mov_b32 m0, s67
	s_nop 0
	global_load_lds_dwordx4 v132, s[68:69]
	s_add_i32 m0, s67, 0x2000
	s_nop 0
	global_load_lds_dwordx4 v128, s[68:69]
	s_mov_b32 m0, s46
	s_nop 0
	global_load_lds_dwordx4 v134, s[44:45]
	s_mov_b32 m0, s47
	s_nop 0
	global_load_lds_dwordx4 v130, s[44:45]
	s_waitcnt vmcnt(8)
	s_waitcnt lgkmcnt(0)
	s_barrier
	s_waitcnt lgkmcnt(0)
	v_mfma_f32_16x16x32_bf16 v[60:63], v[160:163], v[192:195], 0
	v_mfma_f32_16x16x32_bf16 v[56:59], v[168:171], v[192:195], 0
	v_mfma_f32_16x16x32_bf16 v[44:47], v[160:163], v[200:203], 0
	v_mfma_f32_16x16x32_bf16 v[40:43], v[168:171], v[200:203], 0
	v_mfma_f32_16x16x32_bf16 v[28:31], v[160:163], v[218:221], 0
	v_mfma_f32_16x16x32_bf16 v[24:27], v[168:171], v[218:221], 0
	v_mfma_f32_16x16x32_bf16 v[12:15], v[160:163], v[226:229], 0
	v_mfma_f32_16x16x32_bf16 v[8:11], v[168:171], v[226:229], 0
	v_mfma_f32_16x16x32_bf16 v[60:63], v[164:167], v[196:199], v[60:63]
	v_mfma_f32_16x16x32_bf16 v[56:59], v[172:175], v[196:199], v[56:59]
	v_mfma_f32_16x16x32_bf16 v[44:47], v[164:167], v[204:207], v[44:47]
	v_mfma_f32_16x16x32_bf16 v[40:43], v[172:175], v[204:207], v[40:43]
	v_mfma_f32_16x16x32_bf16 v[28:31], v[164:167], v[222:225], v[28:31]
	v_mfma_f32_16x16x32_bf16 v[24:27], v[172:175], v[222:225], v[24:27]
	v_mfma_f32_16x16x32_bf16 v[12:15], v[164:167], v[230:233], v[12:15]
	v_mfma_f32_16x16x32_bf16 v[8:11], v[172:175], v[230:233], v[8:11]
	v_mfma_f32_16x16x32_bf16 v[52:55], v[176:179], v[192:195], 0
	v_mfma_f32_16x16x32_bf16 v[48:51], v[184:187], v[192:195], 0
	v_mfma_f32_16x16x32_bf16 v[36:39], v[176:179], v[200:203], 0
	v_mfma_f32_16x16x32_bf16 v[32:35], v[184:187], v[200:203], 0
	v_mfma_f32_16x16x32_bf16 v[20:23], v[176:179], v[218:221], 0
	v_mfma_f32_16x16x32_bf16 v[16:19], v[184:187], v[218:221], 0
	v_mfma_f32_16x16x32_bf16 v[4:7], v[176:179], v[226:229], 0
	v_mfma_f32_16x16x32_bf16 v[0:3], v[184:187], v[226:229], 0
	v_mfma_f32_16x16x32_bf16 v[52:55], v[180:183], v[196:199], v[52:55]
	v_mfma_f32_16x16x32_bf16 v[48:51], v[188:191], v[196:199], v[48:51]
	v_mfma_f32_16x16x32_bf16 v[36:39], v[180:183], v[204:207], v[36:39]
	v_mfma_f32_16x16x32_bf16 v[32:35], v[188:191], v[204:207], v[32:35]
	v_mfma_f32_16x16x32_bf16 v[20:23], v[180:183], v[222:225], v[20:23]
	v_mfma_f32_16x16x32_bf16 v[16:19], v[188:191], v[222:225], v[16:19]
	v_mfma_f32_16x16x32_bf16 v[4:7], v[180:183], v[230:233], v[4:7]
	v_mfma_f32_16x16x32_bf16 v[0:3], v[188:191], v[230:233], v[0:3]
	s_barrier
	s_branch .Lwin_mid
.LBB0_163:
	s_add_u32 s42, s38, 0x6000
	s_addc_u32 s43, s39, 0
	s_and_b64 s[40:41], s[40:41], exec
	s_cselect_b32 s44, s60, s42
	s_cselect_b32 s45, s29, s43
	s_cselect_b32 s43, s27, s65
	s_cselect_b32 s42, s61, s64
	s_add_u32 s40, s44, 0x8000
	s_addc_u32 s41, s45, 0
	s_add_i32 s67, 0, 0x10000
	v_add_u32_e32 v159, s67, v143
	s_add_i32 s70, 0, 0x14000
	ds_read_b128 v[160:163], v159
	ds_read_b128 v[164:167], v159 offset:1024
	ds_read_b128 v[168:171], v159 offset:2048
	ds_read_b128 v[172:175], v159 offset:3072
	v_add_u32_e32 v159, s70, v143
	ds_read_b128 v[176:179], v159
	ds_read_b128 v[180:183], v159 offset:1024
	ds_read_b128 v[184:187], v159 offset:2048
	ds_read_b128 v[188:191], v159 offset:3072
	s_add_i32 m0, s46, 0xc000
	ds_read_b128 v[192:195], v153
	ds_read_b128 v[196:199], v153 offset:1024
	ds_read_b128 v[200:203], v153 offset:2048
	ds_read_b128 v[204:207], v153 offset:3072
	ds_read_b128 v[218:221], v153 offset:4096
	ds_read_b128 v[222:225], v153 offset:5120
	ds_read_b128 v[226:229], v153 offset:6144
	ds_read_b128 v[230:233], v153 offset:7168
	global_load_lds_dwordx4 v136, s[38:39]
	s_add_i32 m0, s46, 0xe000
	s_nop 0
	global_load_lds_dwordx4 v138, s[38:39]
	s_waitcnt vmcnt(8)
	s_waitcnt lgkmcnt(0)
	s_barrier
	s_waitcnt lgkmcnt(0)
	v_mfma_f32_16x16x32_bf16 v[124:127], v[160:163], v[192:195], v[124:127]
	v_mfma_f32_16x16x32_bf16 v[120:123], v[168:171], v[192:195], v[120:123]
	v_mfma_f32_16x16x32_bf16 v[108:111], v[160:163], v[200:203], v[108:111]
	v_mfma_f32_16x16x32_bf16 v[104:107], v[168:171], v[200:203], v[104:107]
	v_mfma_f32_16x16x32_bf16 v[92:95], v[160:163], v[218:221], v[92:95]
	v_mfma_f32_16x16x32_bf16 v[88:91], v[168:171], v[218:221], v[88:91]
	v_mfma_f32_16x16x32_bf16 v[76:79], v[160:163], v[226:229], v[76:79]
	v_mfma_f32_16x16x32_bf16 v[72:75], v[168:171], v[226:229], v[72:75]
	v_mfma_f32_16x16x32_bf16 v[124:127], v[164:167], v[196:199], v[124:127]
	v_mfma_f32_16x16x32_bf16 v[120:123], v[172:175], v[196:199], v[120:123]
	v_mfma_f32_16x16x32_bf16 v[108:111], v[164:167], v[204:207], v[108:111]
	v_mfma_f32_16x16x32_bf16 v[104:107], v[172:175], v[204:207], v[104:107]
	v_mfma_f32_16x16x32_bf16 v[92:95], v[164:167], v[222:225], v[92:95]
	v_mfma_f32_16x16x32_bf16 v[88:91], v[172:175], v[222:225], v[88:91]
	v_mfma_f32_16x16x32_bf16 v[76:79], v[164:167], v[230:233], v[76:79]
	v_mfma_f32_16x16x32_bf16 v[72:75], v[172:175], v[230:233], v[72:75]
	v_mfma_f32_16x16x32_bf16 v[116:119], v[176:179], v[192:195], v[116:119]
	v_mfma_f32_16x16x32_bf16 v[112:115], v[184:187], v[192:195], v[112:115]
	v_mfma_f32_16x16x32_bf16 v[100:103], v[176:179], v[200:203], v[100:103]
	v_mfma_f32_16x16x32_bf16 v[96:99], v[184:187], v[200:203], v[96:99]
	v_mfma_f32_16x16x32_bf16 v[84:87], v[176:179], v[218:221], v[84:87]
	v_mfma_f32_16x16x32_bf16 v[80:83], v[184:187], v[218:221], v[80:83]
	v_mfma_f32_16x16x32_bf16 v[68:71], v[176:179], v[226:229], v[68:71]
	v_mfma_f32_16x16x32_bf16 v[64:67], v[184:187], v[226:229], v[64:67]
	v_mfma_f32_16x16x32_bf16 v[116:119], v[180:183], v[196:199], v[116:119]
	v_mfma_f32_16x16x32_bf16 v[112:115], v[188:191], v[196:199], v[112:115]
	v_mfma_f32_16x16x32_bf16 v[100:103], v[180:183], v[204:207], v[100:103]
	v_mfma_f32_16x16x32_bf16 v[96:99], v[188:191], v[204:207], v[96:99]
	v_mfma_f32_16x16x32_bf16 v[84:87], v[180:183], v[222:225], v[84:87]
	v_mfma_f32_16x16x32_bf16 v[80:83], v[188:191], v[222:225], v[80:83]
	v_mfma_f32_16x16x32_bf16 v[68:71], v[180:183], v[230:233], v[68:71]
	v_mfma_f32_16x16x32_bf16 v[64:67], v[188:191], v[230:233], v[64:67]
	s_barrier
	s_add_i32 s67, s67, s19
	s_mov_b32 m0, s67
	ds_read_b128 v[192:195], v153 offset:16384
	ds_read_b128 v[196:199], v153 offset:17408
	ds_read_b128 v[200:203], v153 offset:18432
	ds_read_b128 v[204:207], v153 offset:19456
	ds_read_b128 v[218:221], v153 offset:20480
	ds_read_b128 v[222:225], v153 offset:21504
	ds_read_b128 v[226:229], v153 offset:22528
	ds_read_b128 v[230:233], v153 offset:23552
	global_load_lds_dwordx4 v132, s[42:43]
	s_add_i32 m0, s67, 0x2000
	s_add_u32 s68, s42, 0x10000
	s_addc_u32 s69, s43, 0
	s_add_i32 s67, s70, s19
	global_load_lds_dwordx4 v128, s[42:43]
	s_mov_b32 m0, s67
	s_nop 0
	global_load_lds_dwordx4 v132, s[68:69]
	s_add_i32 m0, s67, 0x2000
	s_nop 0
	global_load_lds_dwordx4 v128, s[68:69]
	s_mov_b32 m0, s46
	s_nop 0
	global_load_lds_dwordx4 v134, s[44:45]
	s_mov_b32 m0, s47
	s_nop 0
	global_load_lds_dwordx4 v130, s[44:45]
	s_waitcnt vmcnt(8)
	s_waitcnt lgkmcnt(0)
	s_barrier
	s_waitcnt lgkmcnt(0)
	v_mfma_f32_16x16x32_bf16 v[60:63], v[160:163], v[192:195], v[60:63]
	v_mfma_f32_16x16x32_bf16 v[56:59], v[168:171], v[192:195], v[56:59]
	v_mfma_f32_16x16x32_bf16 v[44:47], v[160:163], v[200:203], v[44:47]
	v_mfma_f32_16x16x32_bf16 v[40:43], v[168:171], v[200:203], v[40:43]
	v_mfma_f32_16x16x32_bf16 v[28:31], v[160:163], v[218:221], v[28:31]
	v_mfma_f32_16x16x32_bf16 v[24:27], v[168:171], v[218:221], v[24:27]
	v_mfma_f32_16x16x32_bf16 v[12:15], v[160:163], v[226:229], v[12:15]
	v_mfma_f32_16x16x32_bf16 v[8:11], v[168:171], v[226:229], v[8:11]
	v_mfma_f32_16x16x32_bf16 v[60:63], v[164:167], v[196:199], v[60:63]
	v_mfma_f32_16x16x32_bf16 v[56:59], v[172:175], v[196:199], v[56:59]
	v_mfma_f32_16x16x32_bf16 v[44:47], v[164:167], v[204:207], v[44:47]
	v_mfma_f32_16x16x32_bf16 v[40:43], v[172:175], v[204:207], v[40:43]
	v_mfma_f32_16x16x32_bf16 v[28:31], v[164:167], v[222:225], v[28:31]
	v_mfma_f32_16x16x32_bf16 v[24:27], v[172:175], v[222:225], v[24:27]
	v_mfma_f32_16x16x32_bf16 v[12:15], v[164:167], v[230:233], v[12:15]
	v_mfma_f32_16x16x32_bf16 v[8:11], v[172:175], v[230:233], v[8:11]
	v_mfma_f32_16x16x32_bf16 v[52:55], v[176:179], v[192:195], v[52:55]
	v_mfma_f32_16x16x32_bf16 v[48:51], v[184:187], v[192:195], v[48:51]
	v_mfma_f32_16x16x32_bf16 v[36:39], v[176:179], v[200:203], v[36:39]
	v_mfma_f32_16x16x32_bf16 v[32:35], v[184:187], v[200:203], v[32:35]
	v_mfma_f32_16x16x32_bf16 v[20:23], v[176:179], v[218:221], v[20:23]
	v_mfma_f32_16x16x32_bf16 v[16:19], v[184:187], v[218:221], v[16:19]
	v_mfma_f32_16x16x32_bf16 v[4:7], v[176:179], v[226:229], v[4:7]
	v_mfma_f32_16x16x32_bf16 v[0:3], v[184:187], v[226:229], v[0:3]
	v_mfma_f32_16x16x32_bf16 v[52:55], v[180:183], v[196:199], v[52:55]
	v_mfma_f32_16x16x32_bf16 v[48:51], v[188:191], v[196:199], v[48:51]
	v_mfma_f32_16x16x32_bf16 v[36:39], v[180:183], v[204:207], v[36:39]
	v_mfma_f32_16x16x32_bf16 v[32:35], v[188:191], v[204:207], v[32:35]
	v_mfma_f32_16x16x32_bf16 v[20:23], v[180:183], v[222:225], v[20:23]
	v_mfma_f32_16x16x32_bf16 v[16:19], v[188:191], v[222:225], v[16:19]
	v_mfma_f32_16x16x32_bf16 v[4:7], v[180:183], v[230:233], v[4:7]
	v_mfma_f32_16x16x32_bf16 v[0:3], v[188:191], v[230:233], v[0:3]
	s_barrier
.Lwin_mid:
	s_add_i32 s67, 0, 0x18000
	v_add_u32_e32 v159, s67, v143
	s_add_i32 s68, 0, 0x1c000
	ds_read_b128 v[160:163], v159
	ds_read_b128 v[164:167], v159 offset:1024
	ds_read_b128 v[168:171], v159 offset:2048
	ds_read_b128 v[172:175], v159 offset:3072
	v_add_u32_e32 v159, s68, v143
	ds_read_b128 v[176:179], v159
	ds_read_b128 v[180:183], v159 offset:1024
	ds_read_b128 v[184:187], v159 offset:2048
	ds_read_b128 v[188:191], v159 offset:3072
	s_add_u32 s44, s44, 0x2000
	s_addc_u32 s45, s45, 0
	s_mov_b32 m0, s48
	ds_read_b128 v[192:195], v153 offset:32768
	ds_read_b128 v[196:199], v153 offset:33792
	ds_read_b128 v[200:203], v153 offset:34816
	ds_read_b128 v[204:207], v153 offset:35840
	ds_read_b128 v[218:221], v153 offset:36864
	ds_read_b128 v[222:225], v153 offset:37888
	ds_read_b128 v[226:229], v153 offset:38912
	ds_read_b128 v[230:233], v153 offset:39936
	global_load_lds_dwordx4 v134, s[44:45]
	s_mov_b32 m0, s49
	s_nop 0
	global_load_lds_dwordx4 v130, s[44:45]
	s_waitcnt vmcnt(8)
	s_waitcnt lgkmcnt(0)
	s_barrier
	s_waitcnt lgkmcnt(0)
	v_mfma_f32_16x16x32_bf16 v[124:127], v[160:163], v[192:195], v[124:127]
	v_mfma_f32_16x16x32_bf16 v[120:123], v[168:171], v[192:195], v[120:123]
	v_mfma_f32_16x16x32_bf16 v[108:111], v[160:163], v[200:203], v[108:111]
	v_mfma_f32_16x16x32_bf16 v[104:107], v[168:171], v[200:203], v[104:107]
	v_mfma_f32_16x16x32_bf16 v[92:95], v[160:163], v[218:221], v[92:95]
	v_mfma_f32_16x16x32_bf16 v[88:91], v[168:171], v[218:221], v[88:91]
	v_mfma_f32_16x16x32_bf16 v[76:79], v[160:163], v[226:229], v[76:79]
	v_mfma_f32_16x16x32_bf16 v[72:75], v[168:171], v[226:229], v[72:75]
	v_mfma_f32_16x16x32_bf16 v[124:127], v[164:167], v[196:199], v[124:127]
	v_mfma_f32_16x16x32_bf16 v[120:123], v[172:175], v[196:199], v[120:123]
	v_mfma_f32_16x16x32_bf16 v[108:111], v[164:167], v[204:207], v[108:111]
	v_mfma_f32_16x16x32_bf16 v[104:107], v[172:175], v[204:207], v[104:107]
	v_mfma_f32_16x16x32_bf16 v[92:95], v[164:167], v[222:225], v[92:95]
	v_mfma_f32_16x16x32_bf16 v[88:91], v[172:175], v[222:225], v[88:91]
	v_mfma_f32_16x16x32_bf16 v[76:79], v[164:167], v[230:233], v[76:79]
	v_mfma_f32_16x16x32_bf16 v[72:75], v[172:175], v[230:233], v[72:75]
	v_mfma_f32_16x16x32_bf16 v[116:119], v[176:179], v[192:195], v[116:119]
	v_mfma_f32_16x16x32_bf16 v[112:115], v[184:187], v[192:195], v[112:115]
	v_mfma_f32_16x16x32_bf16 v[100:103], v[176:179], v[200:203], v[100:103]
	v_mfma_f32_16x16x32_bf16 v[96:99], v[184:187], v[200:203], v[96:99]
	v_mfma_f32_16x16x32_bf16 v[84:87], v[176:179], v[218:221], v[84:87]
	v_mfma_f32_16x16x32_bf16 v[80:83], v[184:187], v[218:221], v[80:83]
	v_mfma_f32_16x16x32_bf16 v[68:71], v[176:179], v[226:229], v[68:71]
	v_mfma_f32_16x16x32_bf16 v[64:67], v[184:187], v[226:229], v[64:67]
	v_mfma_f32_16x16x32_bf16 v[116:119], v[180:183], v[196:199], v[116:119]
	v_mfma_f32_16x16x32_bf16 v[112:115], v[188:191], v[196:199], v[112:115]
	v_mfma_f32_16x16x32_bf16 v[100:103], v[180:183], v[204:207], v[100:103]
	v_mfma_f32_16x16x32_bf16 v[96:99], v[188:191], v[204:207], v[96:99]
	v_mfma_f32_16x16x32_bf16 v[84:87], v[180:183], v[222:225], v[84:87]
	v_mfma_f32_16x16x32_bf16 v[80:83], v[188:191], v[222:225], v[80:83]
	v_mfma_f32_16x16x32_bf16 v[68:71], v[180:183], v[230:233], v[68:71]
	v_mfma_f32_16x16x32_bf16 v[64:67], v[188:191], v[230:233], v[64:67]
	s_barrier
	s_add_i32 s44, s67, s19
	s_add_u32 s98, s42, 0x80
	s_addc_u32 s99, s43, 0
	s_mov_b32 m0, s44
	ds_read_b128 v[192:195], v153 offset:49152
	ds_read_b128 v[196:199], v153 offset:50176
	ds_read_b128 v[200:203], v153 offset:51200
	ds_read_b128 v[204:207], v153 offset:52224
	ds_read_b128 v[218:221], v153 offset:53248
	ds_read_b128 v[222:225], v153 offset:54272
	ds_read_b128 v[226:229], v153 offset:55296
	ds_read_b128 v[230:233], v153 offset:56320
	global_load_lds_dwordx4 v132, s[98:99]
	s_add_i32 m0, s44, 0x2000
	s_add_u32 s42, s42, 0x10080
	s_addc_u32 s43, s43, 0
	s_add_i32 s44, s68, s19
	global_load_lds_dwordx4 v128, s[98:99]
	s_mov_b32 m0, s44
	s_nop 0
	global_load_lds_dwordx4 v132, s[42:43]
	s_add_i32 m0, s44, 0x2000
	s_nop 0
	global_load_lds_dwordx4 v128, s[42:43]
	s_mov_b32 m0, s52
	s_nop 0
	global_load_lds_dwordx4 v134, s[40:41]
	s_mov_b32 m0, s53
	s_nop 0
	global_load_lds_dwordx4 v130, s[40:41]
	s_waitcnt vmcnt(8)
	s_waitcnt lgkmcnt(0)
	s_barrier
	s_waitcnt lgkmcnt(0)
	v_mfma_f32_16x16x32_bf16 v[60:63], v[160:163], v[192:195], v[60:63]
	v_mfma_f32_16x16x32_bf16 v[56:59], v[168:171], v[192:195], v[56:59]
	v_mfma_f32_16x16x32_bf16 v[44:47], v[160:163], v[200:203], v[44:47]
	v_mfma_f32_16x16x32_bf16 v[40:43], v[168:171], v[200:203], v[40:43]
	v_mfma_f32_16x16x32_bf16 v[28:31], v[160:163], v[218:221], v[28:31]
	v_mfma_f32_16x16x32_bf16 v[24:27], v[168:171], v[218:221], v[24:27]
	v_mfma_f32_16x16x32_bf16 v[12:15], v[160:163], v[226:229], v[12:15]
	v_mfma_f32_16x16x32_bf16 v[8:11], v[168:171], v[226:229], v[8:11]
	v_mfma_f32_16x16x32_bf16 v[60:63], v[164:167], v[196:199], v[60:63]
	v_mfma_f32_16x16x32_bf16 v[56:59], v[172:175], v[196:199], v[56:59]
	v_mfma_f32_16x16x32_bf16 v[44:47], v[164:167], v[204:207], v[44:47]
	v_mfma_f32_16x16x32_bf16 v[40:43], v[172:175], v[204:207], v[40:43]
	v_mfma_f32_16x16x32_bf16 v[28:31], v[164:167], v[222:225], v[28:31]
	v_mfma_f32_16x16x32_bf16 v[24:27], v[172:175], v[222:225], v[24:27]
	v_mfma_f32_16x16x32_bf16 v[12:15], v[164:167], v[230:233], v[12:15]
	v_mfma_f32_16x16x32_bf16 v[8:11], v[172:175], v[230:233], v[8:11]
	v_mfma_f32_16x16x32_bf16 v[52:55], v[176:179], v[192:195], v[52:55]
	v_mfma_f32_16x16x32_bf16 v[48:51], v[184:187], v[192:195], v[48:51]
	v_mfma_f32_16x16x32_bf16 v[36:39], v[176:179], v[200:203], v[36:39]
	v_mfma_f32_16x16x32_bf16 v[32:35], v[184:187], v[200:203], v[32:35]
	v_mfma_f32_16x16x32_bf16 v[20:23], v[176:179], v[218:221], v[20:23]
	v_mfma_f32_16x16x32_bf16 v[16:19], v[184:187], v[218:221], v[16:19]
	v_mfma_f32_16x16x32_bf16 v[4:7], v[176:179], v[226:229], v[4:7]
	v_mfma_f32_16x16x32_bf16 v[0:3], v[184:187], v[226:229], v[0:3]
	v_mfma_f32_16x16x32_bf16 v[52:55], v[180:183], v[196:199], v[52:55]
	v_mfma_f32_16x16x32_bf16 v[48:51], v[188:191], v[196:199], v[48:51]
	v_mfma_f32_16x16x32_bf16 v[36:39], v[180:183], v[204:207], v[36:39]
	v_mfma_f32_16x16x32_bf16 v[32:35], v[188:191], v[204:207], v[32:35]
	v_mfma_f32_16x16x32_bf16 v[20:23], v[180:183], v[222:225], v[20:23]
	v_mfma_f32_16x16x32_bf16 v[16:19], v[188:191], v[222:225], v[16:19]
	v_mfma_f32_16x16x32_bf16 v[4:7], v[180:183], v[230:233], v[4:7]
	v_mfma_f32_16x16x32_bf16 v[0:3], v[188:191], v[230:233], v[0:3]
	s_barrier
	s_add_i32 s66, s66, 2
	s_add_u32 s64, s64, 0x100
	s_addc_u32 s65, s65, 0
	s_add_u32 s38, s38, 0x10000
	s_addc_u32 s39, s39, 0
	s_cmp_gt_u32 s66, 13
	s_cbranch_scc1 .LBB0_166

.LBB0_433:
	s_ashr_i32 s61, s60, 31
	s_lshl_b64 s[2:3], s[60:61], 19
	s_add_u32 s70, s50, s2
	s_addc_u32 s71, s51, s3
	s_and_b64 s[2:3], s[36:37], exec
	s_cselect_b32 s2, s71, s35
	s_cselect_b32 s3, s70, s34
	s_ashr_i32 s57, s56, 31
	s_lshl_b64 s[40:41], s[56:57], 19
	s_add_u32 s76, s18, s40
	s_addc_u32 s77, s19, s41
	s_and_b64 s[40:41], s[36:37], exec
	s_cselect_b32 s23, s77, s79
	s_cselect_b32 s29, s76, s78
	s_add_u32 s34, s34, 0x40080
	s_addc_u32 s35, s35, 0
	s_add_u32 s42, s78, 0x100
	v_mov_b32_e32 v0, 0
	s_addc_u32 s43, s79, 0
	s_mov_b32 s44, -2
	s_add_u32 s38, s34, 0xfffc0080
	s_addc_u32 s39, s35, -1
	s_add_i32 s45, 0, 0x10000
	s_cmp_eq_u32 s44, 12
	s_cselect_b32 s41, s2, s39
	s_cselect_b32 s40, s3, s38
	s_cselect_b32 s39, s23, s43
	s_cselect_b32 s38, s29, s42
	s_add_i32 s57, 0, 0x14000
	v_add_u32_e32 v132, s45, v238
	v_add_u32_e32 v148, s57, v238
	ds_read_b128 v[112:115], v132
	ds_read_b128 v[116:119], v132 offset:1024
	ds_read_b128 v[120:123], v132 offset:2048
	ds_read_b128 v[132:135], v132 offset:3072
	ds_read_b128 v[136:139], v148
	ds_read_b128 v[140:143], v148 offset:1024
	ds_read_b128 v[144:147], v148 offset:2048
	ds_read_b128 v[148:151], v148 offset:3072
	s_add_i32 m0, s33, 0xc000
	ds_read_b128 v[152:155], v239
	ds_read_b128 v[156:159], v239 offset:1024
	ds_read_b128 v[168:171], v239 offset:2048
	ds_read_b128 v[172:175], v239 offset:3072
	ds_read_b128 v[176:179], v239 offset:4096
	ds_read_b128 v[180:183], v239 offset:5120
	ds_read_b128 v[184:187], v239 offset:6144
	ds_read_b128 v[188:191], v239 offset:7168
	global_load_lds_dwordx4 v224, s[34:35]
	s_add_i32 m0, s33, 0xe000
	s_nop 0
	global_load_lds_dwordx4 v226, s[34:35]
	s_waitcnt vmcnt(8)
	s_waitcnt lgkmcnt(0)
	s_barrier
	s_waitcnt lgkmcnt(0)
	v_mfma_f32_16x16x32_bf16 v[164:167], v[112:115], v[152:155], 0
	v_mfma_f32_16x16x32_bf16 v[160:163], v[120:123], v[152:155], 0
	v_mfma_f32_16x16x32_bf16 v[108:111], v[112:115], v[168:171], 0
	v_mfma_f32_16x16x32_bf16 v[104:107], v[120:123], v[168:171], 0
	v_mfma_f32_16x16x32_bf16 v[92:95], v[112:115], v[176:179], 0
	v_mfma_f32_16x16x32_bf16 v[88:91], v[120:123], v[176:179], 0
	v_mfma_f32_16x16x32_bf16 v[76:79], v[112:115], v[184:187], 0
	v_mfma_f32_16x16x32_bf16 v[72:75], v[120:123], v[184:187], 0
	v_mfma_f32_16x16x32_bf16 v[164:167], v[116:119], v[156:159], v[164:167]
	v_mfma_f32_16x16x32_bf16 v[160:163], v[132:135], v[156:159], v[160:163]
	v_mfma_f32_16x16x32_bf16 v[108:111], v[116:119], v[172:175], v[108:111]
	v_mfma_f32_16x16x32_bf16 v[104:107], v[132:135], v[172:175], v[104:107]
	v_mfma_f32_16x16x32_bf16 v[92:95], v[116:119], v[180:183], v[92:95]
	v_mfma_f32_16x16x32_bf16 v[88:91], v[132:135], v[180:183], v[88:91]
	v_mfma_f32_16x16x32_bf16 v[76:79], v[116:119], v[188:191], v[76:79]
	v_mfma_f32_16x16x32_bf16 v[72:75], v[132:135], v[188:191], v[72:75]
	v_mfma_f32_16x16x32_bf16 v[128:131], v[136:139], v[152:155], 0
	v_mfma_f32_16x16x32_bf16 v[124:127], v[144:147], v[152:155], 0
	v_mfma_f32_16x16x32_bf16 v[100:103], v[136:139], v[168:171], 0
	v_mfma_f32_16x16x32_bf16 v[96:99], v[144:147], v[168:171], 0
	v_mfma_f32_16x16x32_bf16 v[84:87], v[136:139], v[176:179], 0
	v_mfma_f32_16x16x32_bf16 v[80:83], v[144:147], v[176:179], 0
	v_mfma_f32_16x16x32_bf16 v[68:71], v[136:139], v[184:187], 0
	v_mfma_f32_16x16x32_bf16 v[64:67], v[144:147], v[184:187], 0
	v_mfma_f32_16x16x32_bf16 v[128:131], v[140:143], v[156:159], v[128:131]
	v_mfma_f32_16x16x32_bf16 v[124:127], v[148:151], v[156:159], v[124:127]
	v_mfma_f32_16x16x32_bf16 v[100:103], v[140:143], v[172:175], v[100:103]
	v_mfma_f32_16x16x32_bf16 v[96:99], v[148:151], v[172:175], v[96:99]
	v_mfma_f32_16x16x32_bf16 v[84:87], v[140:143], v[180:183], v[84:87]
	v_mfma_f32_16x16x32_bf16 v[80:83], v[148:151], v[180:183], v[80:83]
	v_mfma_f32_16x16x32_bf16 v[68:71], v[140:143], v[188:191], v[68:71]
	v_mfma_f32_16x16x32_bf16 v[64:67], v[148:151], v[188:191], v[64:67]
	s_barrier
	s_add_i32 s45, s45, s64
	s_mov_b32 m0, s45
	ds_read_b128 v[152:155], v239 offset:16384
	ds_read_b128 v[156:159], v239 offset:17408
	ds_read_b128 v[168:171], v239 offset:18432
	ds_read_b128 v[172:175], v239 offset:19456
	ds_read_b128 v[176:179], v239 offset:20480
	ds_read_b128 v[180:183], v239 offset:21504
	ds_read_b128 v[184:187], v239 offset:22528
	ds_read_b128 v[188:191], v239 offset:23552
	global_load_lds_dwordx4 v208, s[38:39]
	s_add_i32 m0, s45, 0x2000
	s_add_u32 s48, s38, 0x40000
	s_addc_u32 s49, s39, 0
	s_add_i32 s45, s57, s64
	global_load_lds_dwordx4 v222, s[38:39]
	s_mov_b32 m0, s45
	s_nop 0
	global_load_lds_dwordx4 v208, s[48:49]
	s_add_i32 m0, s45, 0x2000
	s_nop 0
	global_load_lds_dwordx4 v222, s[48:49]
	s_add_u32 s100, s40, 0x80
	s_addc_u32 s101, s41, 0
	s_mov_b32 m0, s33
	s_nop 0
	global_load_lds_dwordx4 v218, s[40:41]
	s_mov_b32 m0, s11
	s_nop 0
	global_load_lds_dwordx4 v220, s[40:41]
	s_waitcnt vmcnt(8)
	s_waitcnt lgkmcnt(0)
	s_barrier
	s_waitcnt lgkmcnt(0)
	v_mfma_f32_16x16x32_bf16 v[60:63], v[112:115], v[152:155], 0
	v_mfma_f32_16x16x32_bf16 v[56:59], v[120:123], v[152:155], 0
	v_mfma_f32_16x16x32_bf16 v[44:47], v[112:115], v[168:171], 0
	v_mfma_f32_16x16x32_bf16 v[40:43], v[120:123], v[168:171], 0
	v_mfma_f32_16x16x32_bf16 v[28:31], v[112:115], v[176:179], 0
	v_mfma_f32_16x16x32_bf16 v[24:27], v[120:123], v[176:179], 0
	v_mfma_f32_16x16x32_bf16 v[12:15], v[112:115], v[184:187], 0
	v_mfma_f32_16x16x32_bf16 v[8:11], v[120:123], v[184:187], 0
	v_mfma_f32_16x16x32_bf16 v[60:63], v[116:119], v[156:159], v[60:63]
	v_mfma_f32_16x16x32_bf16 v[56:59], v[132:135], v[156:159], v[56:59]
	v_mfma_f32_16x16x32_bf16 v[44:47], v[116:119], v[172:175], v[44:47]
	v_mfma_f32_16x16x32_bf16 v[40:43], v[132:135], v[172:175], v[40:43]
	v_mfma_f32_16x16x32_bf16 v[28:31], v[116:119], v[180:183], v[28:31]
	v_mfma_f32_16x16x32_bf16 v[24:27], v[132:135], v[180:183], v[24:27]
	v_mfma_f32_16x16x32_bf16 v[12:15], v[116:119], v[188:191], v[12:15]
	v_mfma_f32_16x16x32_bf16 v[8:11], v[132:135], v[188:191], v[8:11]
	v_mfma_f32_16x16x32_bf16 v[52:55], v[136:139], v[152:155], 0
	v_mfma_f32_16x16x32_bf16 v[48:51], v[144:147], v[152:155], 0
	v_mfma_f32_16x16x32_bf16 v[36:39], v[136:139], v[168:171], 0
	v_mfma_f32_16x16x32_bf16 v[32:35], v[144:147], v[168:171], 0
	v_mfma_f32_16x16x32_bf16 v[20:23], v[136:139], v[176:179], 0
	v_mfma_f32_16x16x32_bf16 v[16:19], v[144:147], v[176:179], 0
	v_mfma_f32_16x16x32_bf16 v[4:7], v[136:139], v[184:187], 0
	v_mfma_f32_16x16x32_bf16 v[0:3], v[144:147], v[184:187], 0
	v_mfma_f32_16x16x32_bf16 v[52:55], v[140:143], v[156:159], v[52:55]
	v_mfma_f32_16x16x32_bf16 v[48:51], v[148:151], v[156:159], v[48:51]
	v_mfma_f32_16x16x32_bf16 v[36:39], v[140:143], v[172:175], v[36:39]
	v_mfma_f32_16x16x32_bf16 v[32:35], v[148:151], v[172:175], v[32:35]
	v_mfma_f32_16x16x32_bf16 v[20:23], v[140:143], v[180:183], v[20:23]
	v_mfma_f32_16x16x32_bf16 v[16:19], v[148:151], v[180:183], v[16:19]
	v_mfma_f32_16x16x32_bf16 v[4:7], v[140:143], v[188:191], v[4:7]
	v_mfma_f32_16x16x32_bf16 v[0:3], v[148:151], v[188:191], v[0:3]
	s_barrier
	s_branch .Lwout_mid
.LBB0_434:
	s_add_u32 s38, s34, 0xfffc0080
	s_addc_u32 s39, s35, -1
	s_add_i32 s45, 0, 0x10000
	s_cmp_eq_u32 s44, 12
	s_cselect_b32 s41, s2, s39
	s_cselect_b32 s40, s3, s38
	s_cselect_b32 s39, s23, s43
	s_cselect_b32 s38, s29, s42
	s_add_i32 s57, 0, 0x14000
	v_add_u32_e32 v132, s45, v238
	v_add_u32_e32 v148, s57, v238
	ds_read_b128 v[112:115], v132
	ds_read_b128 v[116:119], v132 offset:1024
	ds_read_b128 v[120:123], v132 offset:2048
	ds_read_b128 v[132:135], v132 offset:3072
	ds_read_b128 v[136:139], v148
	ds_read_b128 v[140:143], v148 offset:1024
	ds_read_b128 v[144:147], v148 offset:2048
	ds_read_b128 v[148:151], v148 offset:3072
	s_add_i32 m0, s33, 0xc000
	ds_read_b128 v[152:155], v239
	ds_read_b128 v[156:159], v239 offset:1024
	ds_read_b128 v[168:171], v239 offset:2048
	ds_read_b128 v[172:175], v239 offset:3072
	ds_read_b128 v[176:179], v239 offset:4096
	ds_read_b128 v[180:183], v239 offset:5120
	ds_read_b128 v[184:187], v239 offset:6144
	ds_read_b128 v[188:191], v239 offset:7168
	global_load_lds_dwordx4 v224, s[34:35]
	s_add_i32 m0, s33, 0xe000
	s_nop 0
	global_load_lds_dwordx4 v226, s[34:35]
	s_waitcnt vmcnt(8)
	s_waitcnt lgkmcnt(0)
	s_barrier
	s_waitcnt lgkmcnt(0)
	v_mfma_f32_16x16x32_bf16 v[164:167], v[112:115], v[152:155], v[164:167]
	v_mfma_f32_16x16x32_bf16 v[160:163], v[120:123], v[152:155], v[160:163]
	v_mfma_f32_16x16x32_bf16 v[108:111], v[112:115], v[168:171], v[108:111]
	v_mfma_f32_16x16x32_bf16 v[104:107], v[120:123], v[168:171], v[104:107]
	v_mfma_f32_16x16x32_bf16 v[92:95], v[112:115], v[176:179], v[92:95]
	v_mfma_f32_16x16x32_bf16 v[88:91], v[120:123], v[176:179], v[88:91]
	v_mfma_f32_16x16x32_bf16 v[76:79], v[112:115], v[184:187], v[76:79]
	v_mfma_f32_16x16x32_bf16 v[72:75], v[120:123], v[184:187], v[72:75]
	v_mfma_f32_16x16x32_bf16 v[164:167], v[116:119], v[156:159], v[164:167]
	v_mfma_f32_16x16x32_bf16 v[160:163], v[132:135], v[156:159], v[160:163]
	v_mfma_f32_16x16x32_bf16 v[108:111], v[116:119], v[172:175], v[108:111]
	v_mfma_f32_16x16x32_bf16 v[104:107], v[132:135], v[172:175], v[104:107]
	v_mfma_f32_16x16x32_bf16 v[92:95], v[116:119], v[180:183], v[92:95]
	v_mfma_f32_16x16x32_bf16 v[88:91], v[132:135], v[180:183], v[88:91]
	v_mfma_f32_16x16x32_bf16 v[76:79], v[116:119], v[188:191], v[76:79]
	v_mfma_f32_16x16x32_bf16 v[72:75], v[132:135], v[188:191], v[72:75]
	v_mfma_f32_16x16x32_bf16 v[128:131], v[136:139], v[152:155], v[128:131]
	v_mfma_f32_16x16x32_bf16 v[124:127], v[144:147], v[152:155], v[124:127]
	v_mfma_f32_16x16x32_bf16 v[100:103], v[136:139], v[168:171], v[100:103]
	v_mfma_f32_16x16x32_bf16 v[96:99], v[144:147], v[168:171], v[96:99]
	v_mfma_f32_16x16x32_bf16 v[84:87], v[136:139], v[176:179], v[84:87]
	v_mfma_f32_16x16x32_bf16 v[80:83], v[144:147], v[176:179], v[80:83]
	v_mfma_f32_16x16x32_bf16 v[68:71], v[136:139], v[184:187], v[68:71]
	v_mfma_f32_16x16x32_bf16 v[64:67], v[144:147], v[184:187], v[64:67]
	v_mfma_f32_16x16x32_bf16 v[128:131], v[140:143], v[156:159], v[128:131]
	v_mfma_f32_16x16x32_bf16 v[124:127], v[148:151], v[156:159], v[124:127]
	v_mfma_f32_16x16x32_bf16 v[100:103], v[140:143], v[172:175], v[100:103]
	v_mfma_f32_16x16x32_bf16 v[96:99], v[148:151], v[172:175], v[96:99]
	v_mfma_f32_16x16x32_bf16 v[84:87], v[140:143], v[180:183], v[84:87]
	v_mfma_f32_16x16x32_bf16 v[80:83], v[148:151], v[180:183], v[80:83]
	v_mfma_f32_16x16x32_bf16 v[68:71], v[140:143], v[188:191], v[68:71]
	v_mfma_f32_16x16x32_bf16 v[64:67], v[148:151], v[188:191], v[64:67]
	s_barrier
	s_add_i32 s45, s45, s64
	s_mov_b32 m0, s45
	ds_read_b128 v[152:155], v239 offset:16384
	ds_read_b128 v[156:159], v239 offset:17408
	ds_read_b128 v[168:171], v239 offset:18432
	ds_read_b128 v[172:175], v239 offset:19456
	ds_read_b128 v[176:179], v239 offset:20480
	ds_read_b128 v[180:183], v239 offset:21504
	ds_read_b128 v[184:187], v239 offset:22528
	ds_read_b128 v[188:191], v239 offset:23552
	global_load_lds_dwordx4 v208, s[38:39]
	s_add_i32 m0, s45, 0x2000
	s_add_u32 s48, s38, 0x40000
	s_addc_u32 s49, s39, 0
	s_add_i32 s45, s57, s64
	global_load_lds_dwordx4 v222, s[38:39]
	s_mov_b32 m0, s45
	s_nop 0
	global_load_lds_dwordx4 v208, s[48:49]
	s_add_i32 m0, s45, 0x2000
	s_nop 0
	global_load_lds_dwordx4 v222, s[48:49]
	s_add_u32 s100, s40, 0x80
	s_addc_u32 s101, s41, 0
	s_mov_b32 m0, s33
	s_nop 0
	global_load_lds_dwordx4 v218, s[40:41]
	s_mov_b32 m0, s11
	s_nop 0
	global_load_lds_dwordx4 v220, s[40:41]
	s_waitcnt vmcnt(8)
	s_waitcnt lgkmcnt(0)
	s_barrier
	s_waitcnt lgkmcnt(0)
	v_mfma_f32_16x16x32_bf16 v[60:63], v[112:115], v[152:155], v[60:63]
	v_mfma_f32_16x16x32_bf16 v[56:59], v[120:123], v[152:155], v[56:59]
	v_mfma_f32_16x16x32_bf16 v[44:47], v[112:115], v[168:171], v[44:47]
	v_mfma_f32_16x16x32_bf16 v[40:43], v[120:123], v[168:171], v[40:43]
	v_mfma_f32_16x16x32_bf16 v[28:31], v[112:115], v[176:179], v[28:31]
	v_mfma_f32_16x16x32_bf16 v[24:27], v[120:123], v[176:179], v[24:27]
	v_mfma_f32_16x16x32_bf16 v[12:15], v[112:115], v[184:187], v[12:15]
	v_mfma_f32_16x16x32_bf16 v[8:11], v[120:123], v[184:187], v[8:11]
	v_mfma_f32_16x16x32_bf16 v[60:63], v[116:119], v[156:159], v[60:63]
	v_mfma_f32_16x16x32_bf16 v[56:59], v[132:135], v[156:159], v[56:59]
	v_mfma_f32_16x16x32_bf16 v[44:47], v[116:119], v[172:175], v[44:47]
	v_mfma_f32_16x16x32_bf16 v[40:43], v[132:135], v[172:175], v[40:43]
	v_mfma_f32_16x16x32_bf16 v[28:31], v[116:119], v[180:183], v[28:31]
	v_mfma_f32_16x16x32_bf16 v[24:27], v[132:135], v[180:183], v[24:27]
	v_mfma_f32_16x16x32_bf16 v[12:15], v[116:119], v[188:191], v[12:15]
	v_mfma_f32_16x16x32_bf16 v[8:11], v[132:135], v[188:191], v[8:11]
	v_mfma_f32_16x16x32_bf16 v[52:55], v[136:139], v[152:155], v[52:55]
	v_mfma_f32_16x16x32_bf16 v[48:51], v[144:147], v[152:155], v[48:51]
	v_mfma_f32_16x16x32_bf16 v[36:39], v[136:139], v[168:171], v[36:39]
	v_mfma_f32_16x16x32_bf16 v[32:35], v[144:147], v[168:171], v[32:35]
	v_mfma_f32_16x16x32_bf16 v[20:23], v[136:139], v[176:179], v[20:23]
	v_mfma_f32_16x16x32_bf16 v[16:19], v[144:147], v[176:179], v[16:19]
	v_mfma_f32_16x16x32_bf16 v[4:7], v[136:139], v[184:187], v[4:7]
	v_mfma_f32_16x16x32_bf16 v[0:3], v[144:147], v[184:187], v[0:3]
	v_mfma_f32_16x16x32_bf16 v[52:55], v[140:143], v[156:159], v[52:55]
	v_mfma_f32_16x16x32_bf16 v[48:51], v[148:151], v[156:159], v[48:51]
	v_mfma_f32_16x16x32_bf16 v[36:39], v[140:143], v[172:175], v[36:39]
	v_mfma_f32_16x16x32_bf16 v[32:35], v[148:151], v[172:175], v[32:35]
	v_mfma_f32_16x16x32_bf16 v[20:23], v[140:143], v[180:183], v[20:23]
	v_mfma_f32_16x16x32_bf16 v[16:19], v[148:151], v[180:183], v[16:19]
	v_mfma_f32_16x16x32_bf16 v[4:7], v[140:143], v[188:191], v[4:7]
	v_mfma_f32_16x16x32_bf16 v[0:3], v[148:151], v[188:191], v[0:3]
	s_barrier
.Lwout_mid:
	s_add_i32 s45, 0, 0x18000
	s_add_i32 s48, 0, 0x1c000
	v_add_u32_e32 v132, s45, v238
	v_add_u32_e32 v148, s48, v238
	ds_read_b128 v[112:115], v132
	ds_read_b128 v[116:119], v132 offset:1024
	ds_read_b128 v[120:123], v132 offset:2048
	ds_read_b128 v[132:135], v132 offset:3072
	ds_read_b128 v[136:139], v148
	ds_read_b128 v[140:143], v148 offset:1024
	ds_read_b128 v[144:147], v148 offset:2048
	ds_read_b128 v[148:151], v148 offset:3072
	s_add_u32 s40, s40, 0x40000
	s_addc_u32 s41, s41, 0
	s_mov_b32 m0, s65
	ds_read_b128 v[152:155], v239 offset:32768
	ds_read_b128 v[156:159], v239 offset:33792
	ds_read_b128 v[168:171], v239 offset:34816
	ds_read_b128 v[172:175], v239 offset:35840
	ds_read_b128 v[176:179], v239 offset:36864
	ds_read_b128 v[180:183], v239 offset:37888
	ds_read_b128 v[184:187], v239 offset:38912
	ds_read_b128 v[188:191], v239 offset:39936
	global_load_lds_dwordx4 v218, s[40:41]
	s_mov_b32 m0, s66
	s_nop 0
	global_load_lds_dwordx4 v220, s[40:41]
	s_waitcnt vmcnt(8)
	s_waitcnt lgkmcnt(0)
	s_barrier
	s_waitcnt lgkmcnt(0)
	v_mfma_f32_16x16x32_bf16 v[164:167], v[112:115], v[152:155], v[164:167]
	v_mfma_f32_16x16x32_bf16 v[160:163], v[120:123], v[152:155], v[160:163]
	v_mfma_f32_16x16x32_bf16 v[108:111], v[112:115], v[168:171], v[108:111]
	v_mfma_f32_16x16x32_bf16 v[104:107], v[120:123], v[168:171], v[104:107]
	v_mfma_f32_16x16x32_bf16 v[92:95], v[112:115], v[176:179], v[92:95]
	v_mfma_f32_16x16x32_bf16 v[88:91], v[120:123], v[176:179], v[88:91]
	v_mfma_f32_16x16x32_bf16 v[76:79], v[112:115], v[184:187], v[76:79]
	v_mfma_f32_16x16x32_bf16 v[72:75], v[120:123], v[184:187], v[72:75]
	v_mfma_f32_16x16x32_bf16 v[164:167], v[116:119], v[156:159], v[164:167]
	v_mfma_f32_16x16x32_bf16 v[160:163], v[132:135], v[156:159], v[160:163]
	v_mfma_f32_16x16x32_bf16 v[108:111], v[116:119], v[172:175], v[108:111]
	v_mfma_f32_16x16x32_bf16 v[104:107], v[132:135], v[172:175], v[104:107]
	v_mfma_f32_16x16x32_bf16 v[92:95], v[116:119], v[180:183], v[92:95]
	v_mfma_f32_16x16x32_bf16 v[88:91], v[132:135], v[180:183], v[88:91]
	v_mfma_f32_16x16x32_bf16 v[76:79], v[116:119], v[188:191], v[76:79]
	v_mfma_f32_16x16x32_bf16 v[72:75], v[132:135], v[188:191], v[72:75]
	v_mfma_f32_16x16x32_bf16 v[128:131], v[136:139], v[152:155], v[128:131]
	v_mfma_f32_16x16x32_bf16 v[124:127], v[144:147], v[152:155], v[124:127]
	v_mfma_f32_16x16x32_bf16 v[100:103], v[136:139], v[168:171], v[100:103]
	v_mfma_f32_16x16x32_bf16 v[96:99], v[144:147], v[168:171], v[96:99]
	v_mfma_f32_16x16x32_bf16 v[84:87], v[136:139], v[176:179], v[84:87]
	v_mfma_f32_16x16x32_bf16 v[80:83], v[144:147], v[176:179], v[80:83]
	v_mfma_f32_16x16x32_bf16 v[68:71], v[136:139], v[184:187], v[68:71]
	v_mfma_f32_16x16x32_bf16 v[64:67], v[144:147], v[184:187], v[64:67]
	v_mfma_f32_16x16x32_bf16 v[128:131], v[140:143], v[156:159], v[128:131]
	v_mfma_f32_16x16x32_bf16 v[124:127], v[148:151], v[156:159], v[124:127]
	v_mfma_f32_16x16x32_bf16 v[100:103], v[140:143], v[172:175], v[100:103]
	v_mfma_f32_16x16x32_bf16 v[96:99], v[148:151], v[172:175], v[96:99]
	v_mfma_f32_16x16x32_bf16 v[84:87], v[140:143], v[180:183], v[84:87]
	v_mfma_f32_16x16x32_bf16 v[80:83], v[148:151], v[180:183], v[80:83]
	v_mfma_f32_16x16x32_bf16 v[68:71], v[140:143], v[188:191], v[68:71]
	v_mfma_f32_16x16x32_bf16 v[64:67], v[148:151], v[188:191], v[64:67]
	s_barrier
	s_add_i32 s40, s45, s64
	s_add_u32 s98, s38, 0x80
	s_addc_u32 s99, s39, 0
	s_mov_b32 m0, s40
	ds_read_b128 v[152:155], v239 offset:49152
	ds_read_b128 v[156:159], v239 offset:50176
	ds_read_b128 v[168:171], v239 offset:51200
	ds_read_b128 v[172:175], v239 offset:52224
	ds_read_b128 v[176:179], v239 offset:53248
	ds_read_b128 v[180:183], v239 offset:54272
	ds_read_b128 v[184:187], v239 offset:55296
	ds_read_b128 v[188:191], v239 offset:56320
	global_load_lds_dwordx4 v208, s[98:99]
	s_add_i32 m0, s40, 0x2000
	s_add_u32 s38, s38, 0x40080
	s_addc_u32 s39, s39, 0
	s_add_i32 s40, s48, s64
	global_load_lds_dwordx4 v222, s[98:99]
	s_mov_b32 m0, s40
	s_nop 0
	global_load_lds_dwordx4 v208, s[38:39]
	s_add_i32 m0, s40, 0x2000
	s_nop 0
	global_load_lds_dwordx4 v222, s[38:39]
	s_mov_b32 m0, s74
	s_nop 0
	global_load_lds_dwordx4 v218, s[100:101]
	s_mov_b32 m0, s75
	s_nop 0
	global_load_lds_dwordx4 v220, s[100:101]
	s_waitcnt vmcnt(8)
	s_waitcnt lgkmcnt(0)
	s_barrier
	s_waitcnt lgkmcnt(0)
	v_mfma_f32_16x16x32_bf16 v[60:63], v[112:115], v[152:155], v[60:63]
	v_mfma_f32_16x16x32_bf16 v[56:59], v[120:123], v[152:155], v[56:59]
	v_mfma_f32_16x16x32_bf16 v[44:47], v[112:115], v[168:171], v[44:47]
	v_mfma_f32_16x16x32_bf16 v[40:43], v[120:123], v[168:171], v[40:43]
	v_mfma_f32_16x16x32_bf16 v[28:31], v[112:115], v[176:179], v[28:31]
	v_mfma_f32_16x16x32_bf16 v[24:27], v[120:123], v[176:179], v[24:27]
	v_mfma_f32_16x16x32_bf16 v[12:15], v[112:115], v[184:187], v[12:15]
	v_mfma_f32_16x16x32_bf16 v[8:11], v[120:123], v[184:187], v[8:11]
	v_mfma_f32_16x16x32_bf16 v[60:63], v[116:119], v[156:159], v[60:63]
	v_mfma_f32_16x16x32_bf16 v[56:59], v[132:135], v[156:159], v[56:59]
	v_mfma_f32_16x16x32_bf16 v[44:47], v[116:119], v[172:175], v[44:47]
	v_mfma_f32_16x16x32_bf16 v[40:43], v[132:135], v[172:175], v[40:43]
	v_mfma_f32_16x16x32_bf16 v[28:31], v[116:119], v[180:183], v[28:31]
	v_mfma_f32_16x16x32_bf16 v[24:27], v[132:135], v[180:183], v[24:27]
	v_mfma_f32_16x16x32_bf16 v[12:15], v[116:119], v[188:191], v[12:15]
	v_mfma_f32_16x16x32_bf16 v[8:11], v[132:135], v[188:191], v[8:11]
	v_mfma_f32_16x16x32_bf16 v[52:55], v[136:139], v[152:155], v[52:55]
	v_mfma_f32_16x16x32_bf16 v[48:51], v[144:147], v[152:155], v[48:51]
	v_mfma_f32_16x16x32_bf16 v[36:39], v[136:139], v[168:171], v[36:39]
	v_mfma_f32_16x16x32_bf16 v[32:35], v[144:147], v[168:171], v[32:35]
	v_mfma_f32_16x16x32_bf16 v[20:23], v[136:139], v[176:179], v[20:23]
	v_mfma_f32_16x16x32_bf16 v[16:19], v[144:147], v[176:179], v[16:19]
	v_mfma_f32_16x16x32_bf16 v[4:7], v[136:139], v[184:187], v[4:7]
	v_mfma_f32_16x16x32_bf16 v[0:3], v[144:147], v[184:187], v[0:3]
	v_mfma_f32_16x16x32_bf16 v[52:55], v[140:143], v[156:159], v[52:55]
	v_mfma_f32_16x16x32_bf16 v[48:51], v[148:151], v[156:159], v[48:51]
	v_mfma_f32_16x16x32_bf16 v[36:39], v[140:143], v[172:175], v[36:39]
	v_mfma_f32_16x16x32_bf16 v[32:35], v[148:151], v[172:175], v[32:35]
	v_mfma_f32_16x16x32_bf16 v[20:23], v[140:143], v[180:183], v[20:23]
	v_mfma_f32_16x16x32_bf16 v[16:19], v[148:151], v[180:183], v[16:19]
	v_mfma_f32_16x16x32_bf16 v[4:7], v[140:143], v[188:191], v[4:7]
	v_mfma_f32_16x16x32_bf16 v[0:3], v[148:151], v[188:191], v[0:3]
	s_barrier
	s_add_i32 s44, s44, 2
	s_add_u32 s42, s42, 0x100
	s_addc_u32 s43, s43, 0
	s_add_u32 s34, s34, 0x100
	s_addc_u32 s35, s35, 0
	s_cmp_gt_u32 s44, 13
	s_cbranch_scc0 .LBB0_434
	s_and_b64 vcc, exec, s[30:31]
	s_cbranch_vccz .LBB0_437
	s_barrier

.LBB0_570:
	s_ashr_i32 s29, s28, 31
	s_lshl_b64 s[30:31], s[28:29], 19
	s_add_u32 s30, s62, s30
	s_addc_u32 s31, s63, s31
	s_and_b64 s[34:35], s[36:37], exec
	s_cselect_b32 s3, s31, s43
	s_cselect_b32 s29, s30, s42
	s_ashr_i32 s27, s26, 31
	s_lshl_b64 s[34:35], s[26:27], 19
	s_add_u32 s34, s17, s34
	s_addc_u32 s35, s18, s35
	s_and_b64 s[44:45], s[36:37], exec
	s_cselect_b32 s27, s35, s41
	s_cselect_b32 s39, s34, s40
	s_add_u32 s61, s40, 0x100
	v_lshl_add_u32 v0, s38, 8, v158
	s_addc_u32 s64, s41, 0
	v_ashrrev_i32_e32 v1, 31, v0
	s_add_u32 s40, s42, 0xa000
	v_mov_b32_e32 v8, 0
	v_lshl_add_u64 v[156:157], v[0:1], 2, s[72:73]
	s_addc_u32 s41, s43, 0
	s_mov_b32 s65, -2
	s_mov_b64 s[42:43], 0
	s_add_u32 s44, s40, 0x6000
	s_addc_u32 s45, s41, 0
	s_and_b64 s[42:43], s[42:43], exec
	s_cselect_b32 s46, s29, s44
	s_cselect_b32 s47, s3, s45
	s_cselect_b32 s45, s27, s64
	s_cselect_b32 s44, s39, s61
	s_add_u32 s42, s46, 0x8000
	s_addc_u32 s43, s47, 0
	s_add_i32 s66, 0, 0x10000
	v_add_u32_e32 v169, s66, v159
	s_add_i32 s68, 0, 0x14000
	ds_read_b128 v[170:173], v169
	ds_read_b128 v[174:177], v169 offset:1024
	ds_read_b128 v[178:181], v169 offset:2048
	ds_read_b128 v[182:185], v169 offset:3072
	v_add_u32_e32 v169, s68, v159
	ds_read_b128 v[186:189], v169
	ds_read_b128 v[190:193], v169 offset:1024
	ds_read_b128 v[194:197], v169 offset:2048
	ds_read_b128 v[198:201], v169 offset:3072
	s_add_i32 m0, s48, 0xc000
	ds_read_b128 v[202:205], v160
	ds_read_b128 v[218:221], v160 offset:1024
	ds_read_b128 v[222:225], v160 offset:2048
	ds_read_b128 v[226:229], v160 offset:3072
	ds_read_b128 v[230:233], v160 offset:4096
	ds_read_b128 v[234:237], v160 offset:5120
	ds_read_b128 v[238:241], v160 offset:6144
	ds_read_b128 v[246:249], v160 offset:7168
	global_load_lds_dwordx4 v152, s[40:41]
	s_add_i32 m0, s48, 0xe000
	s_nop 0
	global_load_lds_dwordx4 v154, s[40:41]
	s_waitcnt vmcnt(8)
	s_waitcnt lgkmcnt(0)
	s_barrier
	s_waitcnt lgkmcnt(0)
	v_mfma_f32_16x16x32_bf16 v[116:119], v[170:173], v[202:205], 0
	v_mfma_f32_16x16x32_bf16 v[124:127], v[178:181], v[202:205], 0
	v_mfma_f32_16x16x32_bf16 v[100:103], v[170:173], v[222:225], 0
	v_mfma_f32_16x16x32_bf16 v[108:111], v[178:181], v[222:225], 0
	v_mfma_f32_16x16x32_bf16 v[84:87], v[170:173], v[230:233], 0
	v_mfma_f32_16x16x32_bf16 v[92:95], v[178:181], v[230:233], 0
	v_mfma_f32_16x16x32_bf16 v[68:71], v[170:173], v[238:241], 0
	v_mfma_f32_16x16x32_bf16 v[76:79], v[178:181], v[238:241], 0
	v_mfma_f32_16x16x32_bf16 v[116:119], v[174:177], v[218:221], v[116:119]
	v_mfma_f32_16x16x32_bf16 v[124:127], v[182:185], v[218:221], v[124:127]
	v_mfma_f32_16x16x32_bf16 v[100:103], v[174:177], v[226:229], v[100:103]
	v_mfma_f32_16x16x32_bf16 v[108:111], v[182:185], v[226:229], v[108:111]
	v_mfma_f32_16x16x32_bf16 v[84:87], v[174:177], v[234:237], v[84:87]
	v_mfma_f32_16x16x32_bf16 v[92:95], v[182:185], v[234:237], v[92:95]
	v_mfma_f32_16x16x32_bf16 v[68:71], v[174:177], v[246:249], v[68:71]
	v_mfma_f32_16x16x32_bf16 v[76:79], v[182:185], v[246:249], v[76:79]
	v_mfma_f32_16x16x32_bf16 v[112:115], v[186:189], v[202:205], 0
	v_mfma_f32_16x16x32_bf16 v[120:123], v[194:197], v[202:205], 0
	v_mfma_f32_16x16x32_bf16 v[96:99], v[186:189], v[222:225], 0
	v_mfma_f32_16x16x32_bf16 v[104:107], v[194:197], v[222:225], 0
	v_mfma_f32_16x16x32_bf16 v[80:83], v[186:189], v[230:233], 0
	v_mfma_f32_16x16x32_bf16 v[88:91], v[194:197], v[230:233], 0
	v_mfma_f32_16x16x32_bf16 v[64:67], v[186:189], v[238:241], 0
	v_mfma_f32_16x16x32_bf16 v[72:75], v[194:197], v[238:241], 0
	v_mfma_f32_16x16x32_bf16 v[112:115], v[190:193], v[218:221], v[112:115]
	v_mfma_f32_16x16x32_bf16 v[120:123], v[198:201], v[218:221], v[120:123]
	v_mfma_f32_16x16x32_bf16 v[96:99], v[190:193], v[226:229], v[96:99]
	v_mfma_f32_16x16x32_bf16 v[104:107], v[198:201], v[226:229], v[104:107]
	v_mfma_f32_16x16x32_bf16 v[80:83], v[190:193], v[234:237], v[80:83]
	v_mfma_f32_16x16x32_bf16 v[88:91], v[198:201], v[234:237], v[88:91]
	v_mfma_f32_16x16x32_bf16 v[64:67], v[190:193], v[246:249], v[64:67]
	v_mfma_f32_16x16x32_bf16 v[72:75], v[198:201], v[246:249], v[72:75]
	s_barrier
	s_add_i32 s66, s66, s19
	s_mov_b32 m0, s66
	ds_read_b128 v[202:205], v160 offset:16384
	ds_read_b128 v[218:221], v160 offset:17408
	ds_read_b128 v[222:225], v160 offset:18432
	ds_read_b128 v[226:229], v160 offset:19456
	ds_read_b128 v[230:233], v160 offset:20480
	ds_read_b128 v[234:237], v160 offset:21504
	ds_read_b128 v[238:241], v160 offset:22528
	ds_read_b128 v[246:249], v160 offset:23552
	global_load_lds_dwordx4 v132, s[44:45]
	s_add_i32 m0, s66, 0x2000
	s_add_u32 s66, s44, 0x40000
	s_addc_u32 s67, s45, 0
	s_add_i32 s68, s68, s19
	global_load_lds_dwordx4 v128, s[44:45]
	s_mov_b32 m0, s68
	s_nop 0
	global_load_lds_dwordx4 v132, s[66:67]
	s_add_i32 m0, s68, 0x2000
	s_nop 0
	global_load_lds_dwordx4 v128, s[66:67]
	s_mov_b32 m0, s48
	s_nop 0
	global_load_lds_dwordx4 v134, s[46:47]
	s_mov_b32 m0, s49
	s_nop 0
	global_load_lds_dwordx4 v130, s[46:47]
	s_waitcnt vmcnt(8)
	s_waitcnt lgkmcnt(0)
	s_barrier
	s_waitcnt lgkmcnt(0)
	v_mfma_f32_16x16x32_bf16 v[52:55], v[170:173], v[202:205], 0
	v_mfma_f32_16x16x32_bf16 v[60:63], v[178:181], v[202:205], 0
	v_mfma_f32_16x16x32_bf16 v[36:39], v[170:173], v[222:225], 0
	v_mfma_f32_16x16x32_bf16 v[44:47], v[178:181], v[222:225], 0
	v_mfma_f32_16x16x32_bf16 v[20:23], v[170:173], v[230:233], 0
	v_mfma_f32_16x16x32_bf16 v[28:31], v[178:181], v[230:233], 0
	v_mfma_f32_16x16x32_bf16 v[4:7], v[170:173], v[238:241], 0
	v_mfma_f32_16x16x32_bf16 v[12:15], v[178:181], v[238:241], 0
	v_mfma_f32_16x16x32_bf16 v[52:55], v[174:177], v[218:221], v[52:55]
	v_mfma_f32_16x16x32_bf16 v[60:63], v[182:185], v[218:221], v[60:63]
	v_mfma_f32_16x16x32_bf16 v[36:39], v[174:177], v[226:229], v[36:39]
	v_mfma_f32_16x16x32_bf16 v[44:47], v[182:185], v[226:229], v[44:47]
	v_mfma_f32_16x16x32_bf16 v[20:23], v[174:177], v[234:237], v[20:23]
	v_mfma_f32_16x16x32_bf16 v[28:31], v[182:185], v[234:237], v[28:31]
	v_mfma_f32_16x16x32_bf16 v[4:7], v[174:177], v[246:249], v[4:7]
	v_mfma_f32_16x16x32_bf16 v[12:15], v[182:185], v[246:249], v[12:15]
	v_mfma_f32_16x16x32_bf16 v[48:51], v[186:189], v[202:205], 0
	v_mfma_f32_16x16x32_bf16 v[56:59], v[194:197], v[202:205], 0
	v_mfma_f32_16x16x32_bf16 v[32:35], v[186:189], v[222:225], 0
	v_mfma_f32_16x16x32_bf16 v[40:43], v[194:197], v[222:225], 0
	v_mfma_f32_16x16x32_bf16 v[16:19], v[186:189], v[230:233], 0
	v_mfma_f32_16x16x32_bf16 v[24:27], v[194:197], v[230:233], 0
	v_mfma_f32_16x16x32_bf16 v[0:3], v[186:189], v[238:241], 0
	v_mfma_f32_16x16x32_bf16 v[8:11], v[194:197], v[238:241], 0
	v_mfma_f32_16x16x32_bf16 v[48:51], v[190:193], v[218:221], v[48:51]
	v_mfma_f32_16x16x32_bf16 v[56:59], v[198:201], v[218:221], v[56:59]
	v_mfma_f32_16x16x32_bf16 v[32:35], v[190:193], v[226:229], v[32:35]
	v_mfma_f32_16x16x32_bf16 v[40:43], v[198:201], v[226:229], v[40:43]
	v_mfma_f32_16x16x32_bf16 v[16:19], v[190:193], v[234:237], v[16:19]
	v_mfma_f32_16x16x32_bf16 v[24:27], v[198:201], v[234:237], v[24:27]
	v_mfma_f32_16x16x32_bf16 v[0:3], v[190:193], v[246:249], v[0:3]
	v_mfma_f32_16x16x32_bf16 v[8:11], v[198:201], v[246:249], v[8:11]
	s_barrier
	s_branch .Lgu_mid
.LBB0_571:
	s_add_u32 s44, s40, 0x6000
	s_addc_u32 s45, s41, 0
	s_and_b64 s[42:43], s[42:43], exec
	s_cselect_b32 s46, s29, s44
	s_cselect_b32 s47, s3, s45
	s_cselect_b32 s45, s27, s64
	s_cselect_b32 s44, s39, s61
	s_add_u32 s42, s46, 0x8000
	s_addc_u32 s43, s47, 0
	s_add_i32 s66, 0, 0x10000
	v_add_u32_e32 v169, s66, v159
	s_add_i32 s68, 0, 0x14000
	ds_read_b128 v[170:173], v169
	ds_read_b128 v[174:177], v169 offset:1024
	ds_read_b128 v[178:181], v169 offset:2048
	ds_read_b128 v[182:185], v169 offset:3072
	v_add_u32_e32 v169, s68, v159
	ds_read_b128 v[186:189], v169
	ds_read_b128 v[190:193], v169 offset:1024
	ds_read_b128 v[194:197], v169 offset:2048
	ds_read_b128 v[198:201], v169 offset:3072
	s_add_i32 m0, s48, 0xc000
	ds_read_b128 v[202:205], v160
	ds_read_b128 v[218:221], v160 offset:1024
	ds_read_b128 v[222:225], v160 offset:2048
	ds_read_b128 v[226:229], v160 offset:3072
	ds_read_b128 v[230:233], v160 offset:4096
	ds_read_b128 v[234:237], v160 offset:5120
	ds_read_b128 v[238:241], v160 offset:6144
	ds_read_b128 v[246:249], v160 offset:7168
	global_load_lds_dwordx4 v152, s[40:41]
	s_add_i32 m0, s48, 0xe000
	s_nop 0
	global_load_lds_dwordx4 v154, s[40:41]
	s_waitcnt vmcnt(8)
	s_waitcnt lgkmcnt(0)
	s_barrier
	s_waitcnt lgkmcnt(0)
	v_mfma_f32_16x16x32_bf16 v[116:119], v[170:173], v[202:205], v[116:119]
	v_mfma_f32_16x16x32_bf16 v[124:127], v[178:181], v[202:205], v[124:127]
	v_mfma_f32_16x16x32_bf16 v[100:103], v[170:173], v[222:225], v[100:103]
	v_mfma_f32_16x16x32_bf16 v[108:111], v[178:181], v[222:225], v[108:111]
	v_mfma_f32_16x16x32_bf16 v[84:87], v[170:173], v[230:233], v[84:87]
	v_mfma_f32_16x16x32_bf16 v[92:95], v[178:181], v[230:233], v[92:95]
	v_mfma_f32_16x16x32_bf16 v[68:71], v[170:173], v[238:241], v[68:71]
	v_mfma_f32_16x16x32_bf16 v[76:79], v[178:181], v[238:241], v[76:79]
	v_mfma_f32_16x16x32_bf16 v[116:119], v[174:177], v[218:221], v[116:119]
	v_mfma_f32_16x16x32_bf16 v[124:127], v[182:185], v[218:221], v[124:127]
	v_mfma_f32_16x16x32_bf16 v[100:103], v[174:177], v[226:229], v[100:103]
	v_mfma_f32_16x16x32_bf16 v[108:111], v[182:185], v[226:229], v[108:111]
	v_mfma_f32_16x16x32_bf16 v[84:87], v[174:177], v[234:237], v[84:87]
	v_mfma_f32_16x16x32_bf16 v[92:95], v[182:185], v[234:237], v[92:95]
	v_mfma_f32_16x16x32_bf16 v[68:71], v[174:177], v[246:249], v[68:71]
	v_mfma_f32_16x16x32_bf16 v[76:79], v[182:185], v[246:249], v[76:79]
	v_mfma_f32_16x16x32_bf16 v[112:115], v[186:189], v[202:205], v[112:115]
	v_mfma_f32_16x16x32_bf16 v[120:123], v[194:197], v[202:205], v[120:123]
	v_mfma_f32_16x16x32_bf16 v[96:99], v[186:189], v[222:225], v[96:99]
	v_mfma_f32_16x16x32_bf16 v[104:107], v[194:197], v[222:225], v[104:107]
	v_mfma_f32_16x16x32_bf16 v[80:83], v[186:189], v[230:233], v[80:83]
	v_mfma_f32_16x16x32_bf16 v[88:91], v[194:197], v[230:233], v[88:91]
	v_mfma_f32_16x16x32_bf16 v[64:67], v[186:189], v[238:241], v[64:67]
	v_mfma_f32_16x16x32_bf16 v[72:75], v[194:197], v[238:241], v[72:75]
	v_mfma_f32_16x16x32_bf16 v[112:115], v[190:193], v[218:221], v[112:115]
	v_mfma_f32_16x16x32_bf16 v[120:123], v[198:201], v[218:221], v[120:123]
	v_mfma_f32_16x16x32_bf16 v[96:99], v[190:193], v[226:229], v[96:99]
	v_mfma_f32_16x16x32_bf16 v[104:107], v[198:201], v[226:229], v[104:107]
	v_mfma_f32_16x16x32_bf16 v[80:83], v[190:193], v[234:237], v[80:83]
	v_mfma_f32_16x16x32_bf16 v[88:91], v[198:201], v[234:237], v[88:91]
	v_mfma_f32_16x16x32_bf16 v[64:67], v[190:193], v[246:249], v[64:67]
	v_mfma_f32_16x16x32_bf16 v[72:75], v[198:201], v[246:249], v[72:75]
	s_barrier
	s_add_i32 s66, s66, s19
	s_mov_b32 m0, s66
	ds_read_b128 v[202:205], v160 offset:16384
	ds_read_b128 v[218:221], v160 offset:17408
	ds_read_b128 v[222:225], v160 offset:18432
	ds_read_b128 v[226:229], v160 offset:19456
	ds_read_b128 v[230:233], v160 offset:20480
	ds_read_b128 v[234:237], v160 offset:21504
	ds_read_b128 v[238:241], v160 offset:22528
	ds_read_b128 v[246:249], v160 offset:23552
	global_load_lds_dwordx4 v132, s[44:45]
	s_add_i32 m0, s66, 0x2000
	s_add_u32 s66, s44, 0x40000
	s_addc_u32 s67, s45, 0
	s_add_i32 s68, s68, s19
	global_load_lds_dwordx4 v128, s[44:45]
	s_mov_b32 m0, s68
	s_nop 0
	global_load_lds_dwordx4 v132, s[66:67]
	s_add_i32 m0, s68, 0x2000
	s_nop 0
	global_load_lds_dwordx4 v128, s[66:67]
	s_mov_b32 m0, s48
	s_nop 0
	global_load_lds_dwordx4 v134, s[46:47]
	s_mov_b32 m0, s49
	s_nop 0
	global_load_lds_dwordx4 v130, s[46:47]
	s_waitcnt vmcnt(8)
	s_waitcnt lgkmcnt(0)
	s_barrier
	s_waitcnt lgkmcnt(0)
	v_mfma_f32_16x16x32_bf16 v[52:55], v[170:173], v[202:205], v[52:55]
	v_mfma_f32_16x16x32_bf16 v[60:63], v[178:181], v[202:205], v[60:63]
	v_mfma_f32_16x16x32_bf16 v[36:39], v[170:173], v[222:225], v[36:39]
	v_mfma_f32_16x16x32_bf16 v[44:47], v[178:181], v[222:225], v[44:47]
	v_mfma_f32_16x16x32_bf16 v[20:23], v[170:173], v[230:233], v[20:23]
	v_mfma_f32_16x16x32_bf16 v[28:31], v[178:181], v[230:233], v[28:31]
	v_mfma_f32_16x16x32_bf16 v[4:7], v[170:173], v[238:241], v[4:7]
	v_mfma_f32_16x16x32_bf16 v[12:15], v[178:181], v[238:241], v[12:15]
	v_mfma_f32_16x16x32_bf16 v[52:55], v[174:177], v[218:221], v[52:55]
	v_mfma_f32_16x16x32_bf16 v[60:63], v[182:185], v[218:221], v[60:63]
	v_mfma_f32_16x16x32_bf16 v[36:39], v[174:177], v[226:229], v[36:39]
	v_mfma_f32_16x16x32_bf16 v[44:47], v[182:185], v[226:229], v[44:47]
	v_mfma_f32_16x16x32_bf16 v[20:23], v[174:177], v[234:237], v[20:23]
	v_mfma_f32_16x16x32_bf16 v[28:31], v[182:185], v[234:237], v[28:31]
	v_mfma_f32_16x16x32_bf16 v[4:7], v[174:177], v[246:249], v[4:7]
	v_mfma_f32_16x16x32_bf16 v[12:15], v[182:185], v[246:249], v[12:15]
	v_mfma_f32_16x16x32_bf16 v[48:51], v[186:189], v[202:205], v[48:51]
	v_mfma_f32_16x16x32_bf16 v[56:59], v[194:197], v[202:205], v[56:59]
	v_mfma_f32_16x16x32_bf16 v[32:35], v[186:189], v[222:225], v[32:35]
	v_mfma_f32_16x16x32_bf16 v[40:43], v[194:197], v[222:225], v[40:43]
	v_mfma_f32_16x16x32_bf16 v[16:19], v[186:189], v[230:233], v[16:19]
	v_mfma_f32_16x16x32_bf16 v[24:27], v[194:197], v[230:233], v[24:27]
	v_mfma_f32_16x16x32_bf16 v[0:3], v[186:189], v[238:241], v[0:3]
	v_mfma_f32_16x16x32_bf16 v[8:11], v[194:197], v[238:241], v[8:11]
	v_mfma_f32_16x16x32_bf16 v[48:51], v[190:193], v[218:221], v[48:51]
	v_mfma_f32_16x16x32_bf16 v[56:59], v[198:201], v[218:221], v[56:59]
	v_mfma_f32_16x16x32_bf16 v[32:35], v[190:193], v[226:229], v[32:35]
	v_mfma_f32_16x16x32_bf16 v[40:43], v[198:201], v[226:229], v[40:43]
	v_mfma_f32_16x16x32_bf16 v[16:19], v[190:193], v[234:237], v[16:19]
	v_mfma_f32_16x16x32_bf16 v[24:27], v[198:201], v[234:237], v[24:27]
	v_mfma_f32_16x16x32_bf16 v[0:3], v[190:193], v[246:249], v[0:3]
	v_mfma_f32_16x16x32_bf16 v[8:11], v[198:201], v[246:249], v[8:11]
	s_barrier
.Lgu_mid:
	s_add_i32 s66, 0, 0x18000
	v_add_u32_e32 v169, s66, v159
	s_add_i32 s67, 0, 0x1c000
	ds_read_b128 v[170:173], v169
	ds_read_b128 v[174:177], v169 offset:1024
	ds_read_b128 v[178:181], v169 offset:2048
	ds_read_b128 v[182:185], v169 offset:3072
	v_add_u32_e32 v169, s67, v159
	ds_read_b128 v[186:189], v169
	ds_read_b128 v[190:193], v169 offset:1024
	ds_read_b128 v[194:197], v169 offset:2048
	ds_read_b128 v[198:201], v169 offset:3072
	s_add_u32 s46, s46, 0x2000
	s_addc_u32 s47, s47, 0
	s_mov_b32 m0, s52
	ds_read_b128 v[202:205], v160 offset:32768
	ds_read_b128 v[218:221], v160 offset:33792
	ds_read_b128 v[222:225], v160 offset:34816
	ds_read_b128 v[226:229], v160 offset:35840
	ds_read_b128 v[230:233], v160 offset:36864
	ds_read_b128 v[234:237], v160 offset:37888
	ds_read_b128 v[238:241], v160 offset:38912
	ds_read_b128 v[246:249], v160 offset:39936
	global_load_lds_dwordx4 v134, s[46:47]
	s_mov_b32 m0, s53
	s_nop 0
	global_load_lds_dwordx4 v130, s[46:47]
	s_waitcnt vmcnt(8)
	s_waitcnt lgkmcnt(0)
	s_barrier
	s_waitcnt lgkmcnt(0)
	v_mfma_f32_16x16x32_bf16 v[116:119], v[170:173], v[202:205], v[116:119]
	v_mfma_f32_16x16x32_bf16 v[124:127], v[178:181], v[202:205], v[124:127]
	v_mfma_f32_16x16x32_bf16 v[100:103], v[170:173], v[222:225], v[100:103]
	v_mfma_f32_16x16x32_bf16 v[108:111], v[178:181], v[222:225], v[108:111]
	v_mfma_f32_16x16x32_bf16 v[84:87], v[170:173], v[230:233], v[84:87]
	v_mfma_f32_16x16x32_bf16 v[92:95], v[178:181], v[230:233], v[92:95]
	v_mfma_f32_16x16x32_bf16 v[68:71], v[170:173], v[238:241], v[68:71]
	v_mfma_f32_16x16x32_bf16 v[76:79], v[178:181], v[238:241], v[76:79]
	v_mfma_f32_16x16x32_bf16 v[116:119], v[174:177], v[218:221], v[116:119]
	v_mfma_f32_16x16x32_bf16 v[124:127], v[182:185], v[218:221], v[124:127]
	v_mfma_f32_16x16x32_bf16 v[100:103], v[174:177], v[226:229], v[100:103]
	v_mfma_f32_16x16x32_bf16 v[108:111], v[182:185], v[226:229], v[108:111]
	v_mfma_f32_16x16x32_bf16 v[84:87], v[174:177], v[234:237], v[84:87]
	v_mfma_f32_16x16x32_bf16 v[92:95], v[182:185], v[234:237], v[92:95]
	v_mfma_f32_16x16x32_bf16 v[68:71], v[174:177], v[246:249], v[68:71]
	v_mfma_f32_16x16x32_bf16 v[76:79], v[182:185], v[246:249], v[76:79]
	v_mfma_f32_16x16x32_bf16 v[112:115], v[186:189], v[202:205], v[112:115]
	v_mfma_f32_16x16x32_bf16 v[120:123], v[194:197], v[202:205], v[120:123]
	v_mfma_f32_16x16x32_bf16 v[96:99], v[186:189], v[222:225], v[96:99]
	v_mfma_f32_16x16x32_bf16 v[104:107], v[194:197], v[222:225], v[104:107]
	v_mfma_f32_16x16x32_bf16 v[80:83], v[186:189], v[230:233], v[80:83]
	v_mfma_f32_16x16x32_bf16 v[88:91], v[194:197], v[230:233], v[88:91]
	v_mfma_f32_16x16x32_bf16 v[64:67], v[186:189], v[238:241], v[64:67]
	v_mfma_f32_16x16x32_bf16 v[72:75], v[194:197], v[238:241], v[72:75]
	v_mfma_f32_16x16x32_bf16 v[112:115], v[190:193], v[218:221], v[112:115]
	v_mfma_f32_16x16x32_bf16 v[120:123], v[198:201], v[218:221], v[120:123]
	v_mfma_f32_16x16x32_bf16 v[96:99], v[190:193], v[226:229], v[96:99]
	v_mfma_f32_16x16x32_bf16 v[104:107], v[198:201], v[226:229], v[104:107]
	v_mfma_f32_16x16x32_bf16 v[80:83], v[190:193], v[234:237], v[80:83]
	v_mfma_f32_16x16x32_bf16 v[88:91], v[198:201], v[234:237], v[88:91]
	v_mfma_f32_16x16x32_bf16 v[64:67], v[190:193], v[246:249], v[64:67]
	v_mfma_f32_16x16x32_bf16 v[72:75], v[198:201], v[246:249], v[72:75]
	s_barrier
	s_add_i32 s46, s66, s19
	s_add_u32 s98, s44, 0x80
	s_addc_u32 s99, s45, 0
	s_mov_b32 m0, s46
	ds_read_b128 v[202:205], v160 offset:49152
	ds_read_b128 v[218:221], v160 offset:50176
	ds_read_b128 v[222:225], v160 offset:51200
	ds_read_b128 v[226:229], v160 offset:52224
	ds_read_b128 v[230:233], v160 offset:53248
	ds_read_b128 v[234:237], v160 offset:54272
	ds_read_b128 v[238:241], v160 offset:55296
	ds_read_b128 v[246:249], v160 offset:56320
	global_load_lds_dwordx4 v132, s[98:99]
	s_add_i32 m0, s46, 0x2000
	s_add_u32 s44, s44, 0x40080
	s_addc_u32 s45, s45, 0
	s_add_i32 s46, s67, s19
	global_load_lds_dwordx4 v128, s[98:99]
	s_mov_b32 m0, s46
	s_nop 0
	global_load_lds_dwordx4 v132, s[44:45]
	s_add_i32 m0, s46, 0x2000
	s_nop 0
	global_load_lds_dwordx4 v128, s[44:45]
	s_mov_b32 m0, s0
	s_nop 0
	global_load_lds_dwordx4 v134, s[42:43]
	s_mov_b32 m0, s56
	s_nop 0
	global_load_lds_dwordx4 v130, s[42:43]
	s_waitcnt vmcnt(8)
	s_waitcnt lgkmcnt(0)
	s_barrier
	s_waitcnt lgkmcnt(0)
	v_mfma_f32_16x16x32_bf16 v[52:55], v[170:173], v[202:205], v[52:55]
	v_mfma_f32_16x16x32_bf16 v[60:63], v[178:181], v[202:205], v[60:63]
	v_mfma_f32_16x16x32_bf16 v[36:39], v[170:173], v[222:225], v[36:39]
	v_mfma_f32_16x16x32_bf16 v[44:47], v[178:181], v[222:225], v[44:47]
	v_mfma_f32_16x16x32_bf16 v[20:23], v[170:173], v[230:233], v[20:23]
	v_mfma_f32_16x16x32_bf16 v[28:31], v[178:181], v[230:233], v[28:31]
	v_mfma_f32_16x16x32_bf16 v[4:7], v[170:173], v[238:241], v[4:7]
	v_mfma_f32_16x16x32_bf16 v[12:15], v[178:181], v[238:241], v[12:15]
	v_mfma_f32_16x16x32_bf16 v[52:55], v[174:177], v[218:221], v[52:55]
	v_mfma_f32_16x16x32_bf16 v[60:63], v[182:185], v[218:221], v[60:63]
	v_mfma_f32_16x16x32_bf16 v[36:39], v[174:177], v[226:229], v[36:39]
	v_mfma_f32_16x16x32_bf16 v[44:47], v[182:185], v[226:229], v[44:47]
	v_mfma_f32_16x16x32_bf16 v[20:23], v[174:177], v[234:237], v[20:23]
	v_mfma_f32_16x16x32_bf16 v[28:31], v[182:185], v[234:237], v[28:31]
	v_mfma_f32_16x16x32_bf16 v[4:7], v[174:177], v[246:249], v[4:7]
	v_mfma_f32_16x16x32_bf16 v[12:15], v[182:185], v[246:249], v[12:15]
	v_mfma_f32_16x16x32_bf16 v[48:51], v[186:189], v[202:205], v[48:51]
	v_mfma_f32_16x16x32_bf16 v[56:59], v[194:197], v[202:205], v[56:59]
	v_mfma_f32_16x16x32_bf16 v[32:35], v[186:189], v[222:225], v[32:35]
	v_mfma_f32_16x16x32_bf16 v[40:43], v[194:197], v[222:225], v[40:43]
	v_mfma_f32_16x16x32_bf16 v[16:19], v[186:189], v[230:233], v[16:19]
	v_mfma_f32_16x16x32_bf16 v[24:27], v[194:197], v[230:233], v[24:27]
	v_mfma_f32_16x16x32_bf16 v[0:3], v[186:189], v[238:241], v[0:3]
	v_mfma_f32_16x16x32_bf16 v[8:11], v[194:197], v[238:241], v[8:11]
	v_mfma_f32_16x16x32_bf16 v[48:51], v[190:193], v[218:221], v[48:51]
	v_mfma_f32_16x16x32_bf16 v[56:59], v[198:201], v[218:221], v[56:59]
	v_mfma_f32_16x16x32_bf16 v[32:35], v[190:193], v[226:229], v[32:35]
	v_mfma_f32_16x16x32_bf16 v[40:43], v[198:201], v[226:229], v[40:43]
	v_mfma_f32_16x16x32_bf16 v[16:19], v[190:193], v[234:237], v[16:19]
	v_mfma_f32_16x16x32_bf16 v[24:27], v[198:201], v[234:237], v[24:27]
	v_mfma_f32_16x16x32_bf16 v[0:3], v[190:193], v[246:249], v[0:3]
	v_mfma_f32_16x16x32_bf16 v[8:11], v[198:201], v[246:249], v[8:11]
	s_barrier
	s_add_i32 s65, s65, 2
	s_add_u32 s61, s61, 0x100
	s_addc_u32 s64, s64, 0
	s_add_u32 s40, s40, 0x10000
	s_addc_u32 s41, s41, 0
	s_cmp_gt_u32 s65, 13
	s_cbranch_scc1 .LBB0_574

.LBB0_653:
	s_add_u32 s34, s34, 0xa000
	s_addc_u32 s35, s35, 0
	s_add_u32 s2, s78, 0x100
	v_mov_b32_e32 v0, 0
	s_addc_u32 s3, s79, 0
	s_mov_b32 s27, -2
	s_waitcnt lgkmcnt(0)
	s_add_u32 s38, s34, 0x6000
	s_addc_u32 s39, s35, 0
	s_cmp_eq_u32 s27, 40
	s_cselect_b32 s42, s56, s38
	s_cselect_b32 s43, s57, s39
	s_cselect_b32 s40, s60, s2
	s_cselect_b32 s41, s61, s3
	s_add_u32 s38, s42, 0x8000
	s_addc_u32 s39, s43, 0
	s_add_i32 s44, 0, 0x10000
	s_add_i32 s46, 0, 0x14000
	v_add_u32_e32 v124, s44, v248
	v_add_u32_e32 v144, s46, v248
	ds_read_b128 v[88:91], v124
	ds_read_b128 v[100:103], v124 offset:1024
	ds_read_b128 v[112:115], v124 offset:2048
	ds_read_b128 v[124:127], v124 offset:3072
	ds_read_b128 v[128:131], v144
	ds_read_b128 v[132:135], v144 offset:1024
	ds_read_b128 v[136:139], v144 offset:2048
	ds_read_b128 v[144:147], v144 offset:3072
	s_add_i32 m0, s95, 0xc000
	ds_read_b128 v[152:155], v249
	ds_read_b128 v[156:159], v249 offset:1024
	ds_read_b128 v[168:171], v249 offset:2048
	ds_read_b128 v[172:175], v249 offset:3072
	ds_read_b128 v[176:179], v249 offset:4096
	ds_read_b128 v[180:183], v249 offset:5120
	ds_read_b128 v[184:187], v249 offset:6144
	ds_read_b128 v[188:191], v249 offset:7168
	global_load_lds_dwordx4 v224, s[34:35]
	s_add_i32 m0, s95, 0xe000
	s_nop 0
	global_load_lds_dwordx4 v226, s[34:35]
	s_waitcnt vmcnt(8)
	s_waitcnt lgkmcnt(0)
	s_barrier
	s_waitcnt lgkmcnt(0)
	v_mfma_f32_16x16x32_bf16 v[164:167], v[88:91], v[152:155], 0
	v_mfma_f32_16x16x32_bf16 v[160:163], v[112:115], v[152:155], 0
	v_mfma_f32_16x16x32_bf16 v[120:123], v[88:91], v[168:171], 0
	v_mfma_f32_16x16x32_bf16 v[116:119], v[112:115], v[168:171], 0
	v_mfma_f32_16x16x32_bf16 v[96:99], v[88:91], v[176:179], 0
	v_mfma_f32_16x16x32_bf16 v[92:95], v[112:115], v[176:179], 0
	v_mfma_f32_16x16x32_bf16 v[76:79], v[88:91], v[184:187], 0
	v_mfma_f32_16x16x32_bf16 v[72:75], v[112:115], v[184:187], 0
	v_mfma_f32_16x16x32_bf16 v[164:167], v[100:103], v[156:159], v[164:167]
	v_mfma_f32_16x16x32_bf16 v[160:163], v[124:127], v[156:159], v[160:163]
	v_mfma_f32_16x16x32_bf16 v[120:123], v[100:103], v[172:175], v[120:123]
	v_mfma_f32_16x16x32_bf16 v[116:119], v[124:127], v[172:175], v[116:119]
	v_mfma_f32_16x16x32_bf16 v[96:99], v[100:103], v[180:183], v[96:99]
	v_mfma_f32_16x16x32_bf16 v[92:95], v[124:127], v[180:183], v[92:95]
	v_mfma_f32_16x16x32_bf16 v[76:79], v[100:103], v[188:191], v[76:79]
	v_mfma_f32_16x16x32_bf16 v[72:75], v[124:127], v[188:191], v[72:75]
	v_mfma_f32_16x16x32_bf16 v[148:151], v[128:131], v[152:155], 0
	v_mfma_f32_16x16x32_bf16 v[140:143], v[136:139], v[152:155], 0
	v_mfma_f32_16x16x32_bf16 v[108:111], v[128:131], v[168:171], 0
	v_mfma_f32_16x16x32_bf16 v[104:107], v[136:139], v[168:171], 0
	v_mfma_f32_16x16x32_bf16 v[84:87], v[128:131], v[176:179], 0
	v_mfma_f32_16x16x32_bf16 v[80:83], v[136:139], v[176:179], 0
	v_mfma_f32_16x16x32_bf16 v[68:71], v[128:131], v[184:187], 0
	v_mfma_f32_16x16x32_bf16 v[64:67], v[136:139], v[184:187], 0
	v_mfma_f32_16x16x32_bf16 v[148:151], v[132:135], v[156:159], v[148:151]
	v_mfma_f32_16x16x32_bf16 v[140:143], v[144:147], v[156:159], v[140:143]
	v_mfma_f32_16x16x32_bf16 v[108:111], v[132:135], v[172:175], v[108:111]
	v_mfma_f32_16x16x32_bf16 v[104:107], v[144:147], v[172:175], v[104:107]
	v_mfma_f32_16x16x32_bf16 v[84:87], v[132:135], v[180:183], v[84:87]
	v_mfma_f32_16x16x32_bf16 v[80:83], v[144:147], v[180:183], v[80:83]
	v_mfma_f32_16x16x32_bf16 v[68:71], v[132:135], v[188:191], v[68:71]
	v_mfma_f32_16x16x32_bf16 v[64:67], v[144:147], v[188:191], v[64:67]
	s_barrier
	s_add_i32 s44, s44, s94
	s_mov_b32 m0, s44
	ds_read_b128 v[152:155], v249 offset:16384
	ds_read_b128 v[156:159], v249 offset:17408
	ds_read_b128 v[168:171], v249 offset:18432
	ds_read_b128 v[172:175], v249 offset:19456
	ds_read_b128 v[176:179], v249 offset:20480
	ds_read_b128 v[180:183], v249 offset:21504
	ds_read_b128 v[184:187], v249 offset:22528
	ds_read_b128 v[188:191], v249 offset:23552
	global_load_lds_dwordx4 v208, s[40:41]
	s_add_i32 m0, s44, 0x2000
	s_add_u32 s44, s40, 0xb0000
	s_addc_u32 s45, s41, 0
	s_add_i32 s46, s46, s94
	global_load_lds_dwordx4 v222, s[40:41]
	s_mov_b32 m0, s46
	s_nop 0
	global_load_lds_dwordx4 v208, s[44:45]
	s_add_i32 m0, s46, 0x2000
	s_nop 0
	global_load_lds_dwordx4 v222, s[44:45]
	s_mov_b32 m0, s95
	s_nop 0
	global_load_lds_dwordx4 v218, s[42:43]
	s_mov_b32 m0, s18
	s_nop 0
	global_load_lds_dwordx4 v220, s[42:43]
	s_waitcnt vmcnt(8)
	s_waitcnt lgkmcnt(0)
	s_barrier
	s_waitcnt lgkmcnt(0)
	v_mfma_f32_16x16x32_bf16 v[60:63], v[88:91], v[152:155], 0
	v_mfma_f32_16x16x32_bf16 v[56:59], v[112:115], v[152:155], 0
	v_mfma_f32_16x16x32_bf16 v[44:47], v[88:91], v[168:171], 0
	v_mfma_f32_16x16x32_bf16 v[40:43], v[112:115], v[168:171], 0
	v_mfma_f32_16x16x32_bf16 v[28:31], v[88:91], v[176:179], 0
	v_mfma_f32_16x16x32_bf16 v[24:27], v[112:115], v[176:179], 0
	v_mfma_f32_16x16x32_bf16 v[12:15], v[88:91], v[184:187], 0
	v_mfma_f32_16x16x32_bf16 v[8:11], v[112:115], v[184:187], 0
	v_mfma_f32_16x16x32_bf16 v[60:63], v[100:103], v[156:159], v[60:63]
	v_mfma_f32_16x16x32_bf16 v[56:59], v[124:127], v[156:159], v[56:59]
	v_mfma_f32_16x16x32_bf16 v[44:47], v[100:103], v[172:175], v[44:47]
	v_mfma_f32_16x16x32_bf16 v[40:43], v[124:127], v[172:175], v[40:43]
	v_mfma_f32_16x16x32_bf16 v[28:31], v[100:103], v[180:183], v[28:31]
	v_mfma_f32_16x16x32_bf16 v[24:27], v[124:127], v[180:183], v[24:27]
	v_mfma_f32_16x16x32_bf16 v[12:15], v[100:103], v[188:191], v[12:15]
	v_mfma_f32_16x16x32_bf16 v[8:11], v[124:127], v[188:191], v[8:11]
	v_mfma_f32_16x16x32_bf16 v[52:55], v[128:131], v[152:155], 0
	v_mfma_f32_16x16x32_bf16 v[48:51], v[136:139], v[152:155], 0
	v_mfma_f32_16x16x32_bf16 v[36:39], v[128:131], v[168:171], 0
	v_mfma_f32_16x16x32_bf16 v[32:35], v[136:139], v[168:171], 0
	v_mfma_f32_16x16x32_bf16 v[20:23], v[128:131], v[176:179], 0
	v_mfma_f32_16x16x32_bf16 v[16:19], v[136:139], v[176:179], 0
	v_mfma_f32_16x16x32_bf16 v[4:7], v[128:131], v[184:187], 0
	v_mfma_f32_16x16x32_bf16 v[0:3], v[136:139], v[184:187], 0
	v_mfma_f32_16x16x32_bf16 v[52:55], v[132:135], v[156:159], v[52:55]
	v_mfma_f32_16x16x32_bf16 v[48:51], v[144:147], v[156:159], v[48:51]
	v_mfma_f32_16x16x32_bf16 v[36:39], v[132:135], v[172:175], v[36:39]
	v_mfma_f32_16x16x32_bf16 v[32:35], v[144:147], v[172:175], v[32:35]
	v_mfma_f32_16x16x32_bf16 v[20:23], v[132:135], v[180:183], v[20:23]
	v_mfma_f32_16x16x32_bf16 v[16:19], v[144:147], v[180:183], v[16:19]
	v_mfma_f32_16x16x32_bf16 v[4:7], v[132:135], v[188:191], v[4:7]
	v_mfma_f32_16x16x32_bf16 v[0:3], v[144:147], v[188:191], v[0:3]
	s_barrier
	s_branch .Ldown_mid
.LBB0_654:
	s_add_u32 s38, s34, 0x6000
	s_addc_u32 s39, s35, 0
	s_cmp_eq_u32 s27, 40
	s_cselect_b32 s42, s56, s38
	s_cselect_b32 s43, s57, s39
	s_cselect_b32 s40, s60, s2
	s_cselect_b32 s41, s61, s3
	s_add_u32 s38, s42, 0x8000
	s_addc_u32 s39, s43, 0
	s_add_i32 s44, 0, 0x10000
	s_add_i32 s46, 0, 0x14000
	v_add_u32_e32 v124, s44, v248
	v_add_u32_e32 v144, s46, v248
	ds_read_b128 v[88:91], v124
	ds_read_b128 v[100:103], v124 offset:1024
	ds_read_b128 v[112:115], v124 offset:2048
	ds_read_b128 v[124:127], v124 offset:3072
	ds_read_b128 v[128:131], v144
	ds_read_b128 v[132:135], v144 offset:1024
	ds_read_b128 v[136:139], v144 offset:2048
	ds_read_b128 v[144:147], v144 offset:3072
	s_add_i32 m0, s95, 0xc000
	ds_read_b128 v[152:155], v249
	ds_read_b128 v[156:159], v249 offset:1024
	ds_read_b128 v[168:171], v249 offset:2048
	ds_read_b128 v[172:175], v249 offset:3072
	ds_read_b128 v[176:179], v249 offset:4096
	ds_read_b128 v[180:183], v249 offset:5120
	ds_read_b128 v[184:187], v249 offset:6144
	ds_read_b128 v[188:191], v249 offset:7168
	global_load_lds_dwordx4 v224, s[34:35]
	s_add_i32 m0, s95, 0xe000
	s_nop 0
	global_load_lds_dwordx4 v226, s[34:35]
	s_waitcnt vmcnt(8)
	s_waitcnt lgkmcnt(0)
	s_barrier
	s_waitcnt lgkmcnt(0)
	v_mfma_f32_16x16x32_bf16 v[164:167], v[88:91], v[152:155], v[164:167]
	v_mfma_f32_16x16x32_bf16 v[160:163], v[112:115], v[152:155], v[160:163]
	v_mfma_f32_16x16x32_bf16 v[120:123], v[88:91], v[168:171], v[120:123]
	v_mfma_f32_16x16x32_bf16 v[116:119], v[112:115], v[168:171], v[116:119]
	v_mfma_f32_16x16x32_bf16 v[96:99], v[88:91], v[176:179], v[96:99]
	v_mfma_f32_16x16x32_bf16 v[92:95], v[112:115], v[176:179], v[92:95]
	v_mfma_f32_16x16x32_bf16 v[76:79], v[88:91], v[184:187], v[76:79]
	v_mfma_f32_16x16x32_bf16 v[72:75], v[112:115], v[184:187], v[72:75]
	v_mfma_f32_16x16x32_bf16 v[164:167], v[100:103], v[156:159], v[164:167]
	v_mfma_f32_16x16x32_bf16 v[160:163], v[124:127], v[156:159], v[160:163]
	v_mfma_f32_16x16x32_bf16 v[120:123], v[100:103], v[172:175], v[120:123]
	v_mfma_f32_16x16x32_bf16 v[116:119], v[124:127], v[172:175], v[116:119]
	v_mfma_f32_16x16x32_bf16 v[96:99], v[100:103], v[180:183], v[96:99]
	v_mfma_f32_16x16x32_bf16 v[92:95], v[124:127], v[180:183], v[92:95]
	v_mfma_f32_16x16x32_bf16 v[76:79], v[100:103], v[188:191], v[76:79]
	v_mfma_f32_16x16x32_bf16 v[72:75], v[124:127], v[188:191], v[72:75]
	v_mfma_f32_16x16x32_bf16 v[148:151], v[128:131], v[152:155], v[148:151]
	v_mfma_f32_16x16x32_bf16 v[140:143], v[136:139], v[152:155], v[140:143]
	v_mfma_f32_16x16x32_bf16 v[108:111], v[128:131], v[168:171], v[108:111]
	v_mfma_f32_16x16x32_bf16 v[104:107], v[136:139], v[168:171], v[104:107]
	v_mfma_f32_16x16x32_bf16 v[84:87], v[128:131], v[176:179], v[84:87]
	v_mfma_f32_16x16x32_bf16 v[80:83], v[136:139], v[176:179], v[80:83]
	v_mfma_f32_16x16x32_bf16 v[68:71], v[128:131], v[184:187], v[68:71]
	v_mfma_f32_16x16x32_bf16 v[64:67], v[136:139], v[184:187], v[64:67]
	v_mfma_f32_16x16x32_bf16 v[148:151], v[132:135], v[156:159], v[148:151]
	v_mfma_f32_16x16x32_bf16 v[140:143], v[144:147], v[156:159], v[140:143]
	v_mfma_f32_16x16x32_bf16 v[108:111], v[132:135], v[172:175], v[108:111]
	v_mfma_f32_16x16x32_bf16 v[104:107], v[144:147], v[172:175], v[104:107]
	v_mfma_f32_16x16x32_bf16 v[84:87], v[132:135], v[180:183], v[84:87]
	v_mfma_f32_16x16x32_bf16 v[80:83], v[144:147], v[180:183], v[80:83]
	v_mfma_f32_16x16x32_bf16 v[68:71], v[132:135], v[188:191], v[68:71]
	v_mfma_f32_16x16x32_bf16 v[64:67], v[144:147], v[188:191], v[64:67]
	s_barrier
	s_add_i32 s44, s44, s94
	s_mov_b32 m0, s44
	ds_read_b128 v[152:155], v249 offset:16384
	ds_read_b128 v[156:159], v249 offset:17408
	ds_read_b128 v[168:171], v249 offset:18432
	ds_read_b128 v[172:175], v249 offset:19456
	ds_read_b128 v[176:179], v249 offset:20480
	ds_read_b128 v[180:183], v249 offset:21504
	ds_read_b128 v[184:187], v249 offset:22528
	ds_read_b128 v[188:191], v249 offset:23552
	global_load_lds_dwordx4 v208, s[40:41]
	s_add_i32 m0, s44, 0x2000
	s_add_u32 s44, s40, 0xb0000
	s_addc_u32 s45, s41, 0
	s_add_i32 s46, s46, s94
	global_load_lds_dwordx4 v222, s[40:41]
	s_mov_b32 m0, s46
	s_nop 0
	global_load_lds_dwordx4 v208, s[44:45]
	s_add_i32 m0, s46, 0x2000
	s_nop 0
	global_load_lds_dwordx4 v222, s[44:45]
	s_mov_b32 m0, s95
	s_nop 0
	global_load_lds_dwordx4 v218, s[42:43]
	s_mov_b32 m0, s18
	s_nop 0
	global_load_lds_dwordx4 v220, s[42:43]
	s_waitcnt vmcnt(8)
	s_waitcnt lgkmcnt(0)
	s_barrier
	s_waitcnt lgkmcnt(0)
	v_mfma_f32_16x16x32_bf16 v[60:63], v[88:91], v[152:155], v[60:63]
	v_mfma_f32_16x16x32_bf16 v[56:59], v[112:115], v[152:155], v[56:59]
	v_mfma_f32_16x16x32_bf16 v[44:47], v[88:91], v[168:171], v[44:47]
	v_mfma_f32_16x16x32_bf16 v[40:43], v[112:115], v[168:171], v[40:43]
	v_mfma_f32_16x16x32_bf16 v[28:31], v[88:91], v[176:179], v[28:31]
	v_mfma_f32_16x16x32_bf16 v[24:27], v[112:115], v[176:179], v[24:27]
	v_mfma_f32_16x16x32_bf16 v[12:15], v[88:91], v[184:187], v[12:15]
	v_mfma_f32_16x16x32_bf16 v[8:11], v[112:115], v[184:187], v[8:11]
	v_mfma_f32_16x16x32_bf16 v[60:63], v[100:103], v[156:159], v[60:63]
	v_mfma_f32_16x16x32_bf16 v[56:59], v[124:127], v[156:159], v[56:59]
	v_mfma_f32_16x16x32_bf16 v[44:47], v[100:103], v[172:175], v[44:47]
	v_mfma_f32_16x16x32_bf16 v[40:43], v[124:127], v[172:175], v[40:43]
	v_mfma_f32_16x16x32_bf16 v[28:31], v[100:103], v[180:183], v[28:31]
	v_mfma_f32_16x16x32_bf16 v[24:27], v[124:127], v[180:183], v[24:27]
	v_mfma_f32_16x16x32_bf16 v[12:15], v[100:103], v[188:191], v[12:15]
	v_mfma_f32_16x16x32_bf16 v[8:11], v[124:127], v[188:191], v[8:11]
	v_mfma_f32_16x16x32_bf16 v[52:55], v[128:131], v[152:155], v[52:55]
	v_mfma_f32_16x16x32_bf16 v[48:51], v[136:139], v[152:155], v[48:51]
	v_mfma_f32_16x16x32_bf16 v[36:39], v[128:131], v[168:171], v[36:39]
	v_mfma_f32_16x16x32_bf16 v[32:35], v[136:139], v[168:171], v[32:35]
	v_mfma_f32_16x16x32_bf16 v[20:23], v[128:131], v[176:179], v[20:23]
	v_mfma_f32_16x16x32_bf16 v[16:19], v[136:139], v[176:179], v[16:19]
	v_mfma_f32_16x16x32_bf16 v[4:7], v[128:131], v[184:187], v[4:7]
	v_mfma_f32_16x16x32_bf16 v[0:3], v[136:139], v[184:187], v[0:3]
	v_mfma_f32_16x16x32_bf16 v[52:55], v[132:135], v[156:159], v[52:55]
	v_mfma_f32_16x16x32_bf16 v[48:51], v[144:147], v[156:159], v[48:51]
	v_mfma_f32_16x16x32_bf16 v[36:39], v[132:135], v[172:175], v[36:39]
	v_mfma_f32_16x16x32_bf16 v[32:35], v[144:147], v[172:175], v[32:35]
	v_mfma_f32_16x16x32_bf16 v[20:23], v[132:135], v[180:183], v[20:23]
	v_mfma_f32_16x16x32_bf16 v[16:19], v[144:147], v[180:183], v[16:19]
	v_mfma_f32_16x16x32_bf16 v[4:7], v[132:135], v[188:191], v[4:7]
	v_mfma_f32_16x16x32_bf16 v[0:3], v[144:147], v[188:191], v[0:3]
	s_barrier
.Ldown_mid:
	s_add_i32 s44, 0, 0x18000
	s_add_i32 s45, 0, 0x1c000
	v_add_u32_e32 v124, s44, v248
	v_add_u32_e32 v144, s45, v248
	ds_read_b128 v[88:91], v124
	ds_read_b128 v[100:103], v124 offset:1024
	ds_read_b128 v[112:115], v124 offset:2048
	ds_read_b128 v[124:127], v124 offset:3072
	ds_read_b128 v[128:131], v144
	ds_read_b128 v[132:135], v144 offset:1024
	ds_read_b128 v[136:139], v144 offset:2048
	ds_read_b128 v[144:147], v144 offset:3072
	s_add_u32 s42, s42, 0x2000
	s_addc_u32 s43, s43, 0
	s_mov_b32 m0, s19
	ds_read_b128 v[152:155], v249 offset:32768
	ds_read_b128 v[156:159], v249 offset:33792
	ds_read_b128 v[168:171], v249 offset:34816
	ds_read_b128 v[172:175], v249 offset:35840
	ds_read_b128 v[176:179], v249 offset:36864
	ds_read_b128 v[180:183], v249 offset:37888
	ds_read_b128 v[184:187], v249 offset:38912
	ds_read_b128 v[188:191], v249 offset:39936
	global_load_lds_dwordx4 v218, s[42:43]
	s_mov_b32 m0, s66
	s_nop 0
	global_load_lds_dwordx4 v220, s[42:43]
	s_waitcnt vmcnt(8)
	s_waitcnt lgkmcnt(0)
	s_barrier
	s_waitcnt lgkmcnt(0)
	v_mfma_f32_16x16x32_bf16 v[164:167], v[88:91], v[152:155], v[164:167]
	v_mfma_f32_16x16x32_bf16 v[160:163], v[112:115], v[152:155], v[160:163]
	v_mfma_f32_16x16x32_bf16 v[120:123], v[88:91], v[168:171], v[120:123]
	v_mfma_f32_16x16x32_bf16 v[116:119], v[112:115], v[168:171], v[116:119]
	v_mfma_f32_16x16x32_bf16 v[96:99], v[88:91], v[176:179], v[96:99]
	v_mfma_f32_16x16x32_bf16 v[92:95], v[112:115], v[176:179], v[92:95]
	v_mfma_f32_16x16x32_bf16 v[76:79], v[88:91], v[184:187], v[76:79]
	v_mfma_f32_16x16x32_bf16 v[72:75], v[112:115], v[184:187], v[72:75]
	v_mfma_f32_16x16x32_bf16 v[164:167], v[100:103], v[156:159], v[164:167]
	v_mfma_f32_16x16x32_bf16 v[160:163], v[124:127], v[156:159], v[160:163]
	v_mfma_f32_16x16x32_bf16 v[120:123], v[100:103], v[172:175], v[120:123]
	v_mfma_f32_16x16x32_bf16 v[116:119], v[124:127], v[172:175], v[116:119]
	v_mfma_f32_16x16x32_bf16 v[96:99], v[100:103], v[180:183], v[96:99]
	v_mfma_f32_16x16x32_bf16 v[92:95], v[124:127], v[180:183], v[92:95]
	v_mfma_f32_16x16x32_bf16 v[76:79], v[100:103], v[188:191], v[76:79]
	v_mfma_f32_16x16x32_bf16 v[72:75], v[124:127], v[188:191], v[72:75]
	v_mfma_f32_16x16x32_bf16 v[148:151], v[128:131], v[152:155], v[148:151]
	v_mfma_f32_16x16x32_bf16 v[140:143], v[136:139], v[152:155], v[140:143]
	v_mfma_f32_16x16x32_bf16 v[108:111], v[128:131], v[168:171], v[108:111]
	v_mfma_f32_16x16x32_bf16 v[104:107], v[136:139], v[168:171], v[104:107]
	v_mfma_f32_16x16x32_bf16 v[84:87], v[128:131], v[176:179], v[84:87]
	v_mfma_f32_16x16x32_bf16 v[80:83], v[136:139], v[176:179], v[80:83]
	v_mfma_f32_16x16x32_bf16 v[68:71], v[128:131], v[184:187], v[68:71]
	v_mfma_f32_16x16x32_bf16 v[64:67], v[136:139], v[184:187], v[64:67]
	v_mfma_f32_16x16x32_bf16 v[148:151], v[132:135], v[156:159], v[148:151]
	v_mfma_f32_16x16x32_bf16 v[140:143], v[144:147], v[156:159], v[140:143]
	v_mfma_f32_16x16x32_bf16 v[108:111], v[132:135], v[172:175], v[108:111]
	v_mfma_f32_16x16x32_bf16 v[104:107], v[144:147], v[172:175], v[104:107]
	v_mfma_f32_16x16x32_bf16 v[84:87], v[132:135], v[180:183], v[84:87]
	v_mfma_f32_16x16x32_bf16 v[80:83], v[144:147], v[180:183], v[80:83]
	v_mfma_f32_16x16x32_bf16 v[68:71], v[132:135], v[188:191], v[68:71]
	v_mfma_f32_16x16x32_bf16 v[64:67], v[144:147], v[188:191], v[64:67]
	s_barrier
	s_add_i32 s42, s44, s94
	s_add_u32 s98, s40, 0x80
	s_addc_u32 s99, s41, 0
	s_mov_b32 m0, s42
	ds_read_b128 v[152:155], v249 offset:49152
	ds_read_b128 v[156:159], v249 offset:50176
	ds_read_b128 v[168:171], v249 offset:51200
	ds_read_b128 v[172:175], v249 offset:52224
	ds_read_b128 v[176:179], v249 offset:53248
	ds_read_b128 v[180:183], v249 offset:54272
	ds_read_b128 v[184:187], v249 offset:55296
	ds_read_b128 v[188:191], v249 offset:56320
	global_load_lds_dwordx4 v208, s[98:99]
	s_add_i32 m0, s42, 0x2000
	s_add_u32 s40, s40, 0xb0080
	s_addc_u32 s41, s41, 0
	s_add_i32 s42, s45, s94
	global_load_lds_dwordx4 v222, s[98:99]
	s_mov_b32 m0, s42
	s_nop 0
	global_load_lds_dwordx4 v208, s[40:41]
	s_add_i32 m0, s42, 0x2000
	s_nop 0
	global_load_lds_dwordx4 v222, s[40:41]
	s_mov_b32 m0, s72
	s_nop 0
	global_load_lds_dwordx4 v218, s[38:39]
	s_mov_b32 m0, s73
	s_nop 0
	global_load_lds_dwordx4 v220, s[38:39]
	s_waitcnt vmcnt(8)
	s_waitcnt lgkmcnt(0)
	s_barrier
	s_waitcnt lgkmcnt(0)
	v_mfma_f32_16x16x32_bf16 v[60:63], v[88:91], v[152:155], v[60:63]
	v_mfma_f32_16x16x32_bf16 v[56:59], v[112:115], v[152:155], v[56:59]
	v_mfma_f32_16x16x32_bf16 v[44:47], v[88:91], v[168:171], v[44:47]
	v_mfma_f32_16x16x32_bf16 v[40:43], v[112:115], v[168:171], v[40:43]
	v_mfma_f32_16x16x32_bf16 v[28:31], v[88:91], v[176:179], v[28:31]
	v_mfma_f32_16x16x32_bf16 v[24:27], v[112:115], v[176:179], v[24:27]
	v_mfma_f32_16x16x32_bf16 v[12:15], v[88:91], v[184:187], v[12:15]
	v_mfma_f32_16x16x32_bf16 v[8:11], v[112:115], v[184:187], v[8:11]
	v_mfma_f32_16x16x32_bf16 v[60:63], v[100:103], v[156:159], v[60:63]
	v_mfma_f32_16x16x32_bf16 v[56:59], v[124:127], v[156:159], v[56:59]
	v_mfma_f32_16x16x32_bf16 v[44:47], v[100:103], v[172:175], v[44:47]
	v_mfma_f32_16x16x32_bf16 v[40:43], v[124:127], v[172:175], v[40:43]
	v_mfma_f32_16x16x32_bf16 v[28:31], v[100:103], v[180:183], v[28:31]
	v_mfma_f32_16x16x32_bf16 v[24:27], v[124:127], v[180:183], v[24:27]
	v_mfma_f32_16x16x32_bf16 v[12:15], v[100:103], v[188:191], v[12:15]
	v_mfma_f32_16x16x32_bf16 v[8:11], v[124:127], v[188:191], v[8:11]
	v_mfma_f32_16x16x32_bf16 v[52:55], v[128:131], v[152:155], v[52:55]
	v_mfma_f32_16x16x32_bf16 v[48:51], v[136:139], v[152:155], v[48:51]
	v_mfma_f32_16x16x32_bf16 v[36:39], v[128:131], v[168:171], v[36:39]
	v_mfma_f32_16x16x32_bf16 v[32:35], v[136:139], v[168:171], v[32:35]
	v_mfma_f32_16x16x32_bf16 v[20:23], v[128:131], v[176:179], v[20:23]
	v_mfma_f32_16x16x32_bf16 v[16:19], v[136:139], v[176:179], v[16:19]
	v_mfma_f32_16x16x32_bf16 v[4:7], v[128:131], v[184:187], v[4:7]
	v_mfma_f32_16x16x32_bf16 v[0:3], v[136:139], v[184:187], v[0:3]
	v_mfma_f32_16x16x32_bf16 v[52:55], v[132:135], v[156:159], v[52:55]
	v_mfma_f32_16x16x32_bf16 v[48:51], v[144:147], v[156:159], v[48:51]
	v_mfma_f32_16x16x32_bf16 v[36:39], v[132:135], v[172:175], v[36:39]
	v_mfma_f32_16x16x32_bf16 v[32:35], v[144:147], v[172:175], v[32:35]
	v_mfma_f32_16x16x32_bf16 v[20:23], v[132:135], v[180:183], v[20:23]
	v_mfma_f32_16x16x32_bf16 v[16:19], v[144:147], v[180:183], v[16:19]
	v_mfma_f32_16x16x32_bf16 v[4:7], v[132:135], v[188:191], v[4:7]
	v_mfma_f32_16x16x32_bf16 v[0:3], v[144:147], v[188:191], v[0:3]
	s_barrier
	s_add_i32 s27, s27, 2
	s_add_u32 s2, s2, 0x100
	s_addc_u32 s3, s3, 0
	s_add_u32 s34, s34, 0x10000
	s_addc_u32 s35, s35, 0
	s_cmp_gt_u32 s27, 41
	s_cbranch_scc0 .LBB0_654
	s_and_b64 vcc, exec, s[76:77]
	s_cbranch_vccz .LBB0_657
	s_barrier
